# hyena: hand-written fft_mid (last fwd pass + spectrum multiply + first inv pass), H loads batched 4 at a time
# speedup vs baseline: 1.0220x; 1.0012x over previous
; HD float2 cmul(float2 a, float2 b){ return make_float2(a.x*b.x - a.y*b.y, a.x*b.y + a.y*b.x); }
; HD float2 cmulc(float2 a, float2 b){ return make_float2(a.x*b.x + a.y*b.y, a.y*b.x - a.x*b.y); }
; template<bool INV, bool NOTW>
; HD void bf4c(float2* Z, int i0, int i1, int i2, int i3, float2 w1, float2 w2, float2 w3){
;   float2 a0=Z[i0], a1=Z[i1], a2=Z[i2], a3=Z[i3];
;   if (INV && !NOTW){ a1=cmulc(a1,w1); a2=cmulc(a2,w2); a3=cmulc(a3,w3); }
;   float2 s02=make_float2(a0.x+a2.x,a0.y+a2.y), d02=make_float2(a0.x-a2.x,a0.y-a2.y);
;   float2 s13=make_float2(a1.x+a3.x,a1.y+a3.y), d13=make_float2(a1.x-a3.x,a1.y-a3.y);
;   float2 y0=make_float2(s02.x+s13.x,s02.y+s13.y), y2=make_float2(s02.x-s13.x,s02.y-s13.y);
;   float2 ym=make_float2(d02.x+d13.y,d02.y-d13.x);
;   float2 yp=make_float2(d02.x-d13.y,d02.y+d13.x);
;   float2 y1, y3;
;   if (INV){ y1=yp; y3=ym; } else if (NOTW){ y1=ym; y3=yp; } else { y1=cmul(ym,w1); y2=cmul(y2,w2); y3=cmul(yp,w3); }
;   Z[i0]=y0; Z[i1]=y1; Z[i2]=y2; Z[i3]=y3;
; template<bool INV, int LQ, bool BARRIER=true>
; HD void fft_pass(float2* Z, const float2* twA, const float2* twB, int tid){
;     ...
;     _Pragma("unroll") for (int e=0;e<2;++e){ int j=tid+512*e; int k=j*tws;
;       float2 w1=cmul(twA[k>>6],twB[k&63]), w2=cmul(w1,w1), w3=cmul(w2,w1);
;       _Pragma("unroll") for (int ip=0;ip<4;++ip){ int base=ip*4096+j; bf4c<INV,false>(Z,base,base+q,base+2*q,base+3*q,w1,w2,w3); } }
.Lmy_pf_skipb:
	v_add_u32_e32 v226, 0, v154
	v_lshrrev_b32_e32 v224, 4, v226
	v_lshlrev_b32_e32 v224, 3, v224
	v_add_u32_e32 v224, 0x20800, v224
	v_and_b32_e32 v225, 15, v226
	v_lshlrev_b32_e32 v225, 5, v225
	v_add_u32_e32 v225, 0x20a00, v225
	ds_read_b64 v[238:239], v224
	ds_read_b64 v[240:241], v225
	s_waitcnt lgkmcnt(0)
	v_mul_f32_e32 v227, v239, v241
	v_fma_f32 v16, v238, v240, -v227
	v_mul_f32_e32 v227, v239, v240
	v_fma_f32 v17, v238, v241, v227
	v_mul_f32_e32 v227, v17, v17
	v_fma_f32 v18, v16, v16, -v227
	v_mul_f32_e32 v227, v17, v16
	v_fma_f32 v19, v16, v17, v227
	v_mul_f32_e32 v227, v19, v17
	v_fma_f32 v20, v18, v16, -v227
	v_mul_f32_e32 v227, v19, v16
	v_fma_f32 v21, v18, v17, v227
	v_lshlrev_b32_e32 v222, 3, v154
	v_add_u32_e32 v223, 0x10000, v222
	ds_read_b64 v[0:1], v222 offset:0
	ds_read_b64 v[2:3], v222 offset:8192
	ds_read_b64 v[4:5], v222 offset:16384
	ds_read_b64 v[6:7], v222 offset:24576
	ds_read_b64 v[8:9], v222 offset:32768
	ds_read_b64 v[10:11], v222 offset:40960
	ds_read_b64 v[12:13], v222 offset:49152
	ds_read_b64 v[14:15], v222 offset:57344
	s_waitcnt lgkmcnt(4)
	v_add_f32_e32 v22, v0, v4
	v_sub_f32_e32 v24, v0, v4
	v_add_f32_e32 v26, v2, v6
	v_sub_f32_e32 v28, v2, v6
	v_add_f32_e32 v23, v1, v5
	v_sub_f32_e32 v25, v1, v5
	v_add_f32_e32 v27, v3, v7
	v_sub_f32_e32 v29, v3, v7
	v_add_f32_e32 v80, v22, v26
	v_add_f32_e32 v81, v23, v27
	ds_write_b64 v222, v[80:81] offset:0
	v_sub_f32_e32 v242, v22, v26
	v_sub_f32_e32 v243, v23, v27
	v_add_f32_e32 v244, v24, v29
	v_sub_f32_e32 v245, v25, v28
	v_sub_f32_e32 v246, v24, v29
	v_add_f32_e32 v247, v25, v28
	v_mul_f32_e32 v227, v245, v17
	v_fma_f32 v82, v244, v16, -v227
	v_mul_f32_e32 v227, v245, v16
	v_fma_f32 v83, v244, v17, v227
	ds_write_b64 v222, v[82:83] offset:8192
	v_mul_f32_e32 v227, v243, v19
	v_fma_f32 v84, v242, v18, -v227
	v_mul_f32_e32 v227, v243, v18
	v_fma_f32 v85, v242, v19, v227
	ds_write_b64 v222, v[84:85] offset:16384
	v_mul_f32_e32 v227, v247, v21
	v_fma_f32 v236, v246, v20, -v227
	v_mul_f32_e32 v227, v247, v20
	v_fma_f32 v237, v246, v21, v227
	ds_write_b64 v222, v[236:237] offset:24576
	ds_read_b64 v[0:1], v223 offset:0
	ds_read_b64 v[2:3], v223 offset:8192
	ds_read_b64 v[4:5], v223 offset:16384
	ds_read_b64 v[6:7], v223 offset:24576
	s_waitcnt lgkmcnt(8)
	v_add_f32_e32 v22, v8, v12
	v_sub_f32_e32 v24, v8, v12
	v_add_f32_e32 v26, v10, v14
	v_sub_f32_e32 v28, v10, v14
	v_add_f32_e32 v23, v9, v13
	v_sub_f32_e32 v25, v9, v13
	v_add_f32_e32 v27, v11, v15
	v_sub_f32_e32 v29, v11, v15
	v_add_f32_e32 v80, v22, v26
	v_add_f32_e32 v81, v23, v27
	ds_write_b64 v222, v[80:81] offset:32768
	v_sub_f32_e32 v242, v22, v26
	v_sub_f32_e32 v243, v23, v27
	v_add_f32_e32 v244, v24, v29
	v_sub_f32_e32 v245, v25, v28
	v_sub_f32_e32 v246, v24, v29
	v_add_f32_e32 v247, v25, v28
	v_mul_f32_e32 v227, v245, v17
	v_fma_f32 v82, v244, v16, -v227
	v_mul_f32_e32 v227, v245, v16
	v_fma_f32 v83, v244, v17, v227
	ds_write_b64 v222, v[82:83] offset:40960
	v_mul_f32_e32 v227, v243, v19
	v_fma_f32 v84, v242, v18, -v227
	v_mul_f32_e32 v227, v243, v18
	v_fma_f32 v85, v242, v19, v227
	ds_write_b64 v222, v[84:85] offset:49152
	v_mul_f32_e32 v227, v247, v21
	v_fma_f32 v236, v246, v20, -v227
	v_mul_f32_e32 v227, v247, v20
	v_fma_f32 v237, v246, v21, v227
	ds_write_b64 v222, v[236:237] offset:57344
	ds_read_b64 v[8:9], v223 offset:32768
	ds_read_b64 v[10:11], v223 offset:40960
	ds_read_b64 v[12:13], v223 offset:49152
	ds_read_b64 v[14:15], v223 offset:57344
	s_waitcnt lgkmcnt(8)
	v_add_f32_e32 v22, v0, v4
	v_sub_f32_e32 v24, v0, v4
	v_add_f32_e32 v26, v2, v6
	v_sub_f32_e32 v28, v2, v6
	v_add_f32_e32 v23, v1, v5
	v_sub_f32_e32 v25, v1, v5
	v_add_f32_e32 v27, v3, v7
	v_sub_f32_e32 v29, v3, v7
	v_add_f32_e32 v80, v22, v26
	v_add_f32_e32 v81, v23, v27
	ds_write_b64 v223, v[80:81] offset:0
	v_sub_f32_e32 v242, v22, v26
	v_sub_f32_e32 v243, v23, v27
	v_add_f32_e32 v244, v24, v29
	v_sub_f32_e32 v245, v25, v28
	v_sub_f32_e32 v246, v24, v29
	v_add_f32_e32 v247, v25, v28
	v_mul_f32_e32 v227, v245, v17
	v_fma_f32 v82, v244, v16, -v227
	v_mul_f32_e32 v227, v245, v16
	v_fma_f32 v83, v244, v17, v227
	ds_write_b64 v223, v[82:83] offset:8192
	v_mul_f32_e32 v227, v243, v19
	v_fma_f32 v84, v242, v18, -v227
	v_mul_f32_e32 v227, v243, v18
	v_fma_f32 v85, v242, v19, v227
	ds_write_b64 v223, v[84:85] offset:16384
	v_mul_f32_e32 v227, v247, v21
	v_fma_f32 v236, v246, v20, -v227
	v_mul_f32_e32 v227, v247, v20
	v_fma_f32 v237, v246, v21, v227
	ds_write_b64 v223, v[236:237] offset:24576
	s_waitcnt lgkmcnt(4)
	v_add_f32_e32 v22, v8, v12
	v_sub_f32_e32 v24, v8, v12
	v_add_f32_e32 v26, v10, v14
	v_sub_f32_e32 v28, v10, v14
	v_add_f32_e32 v23, v9, v13
	v_sub_f32_e32 v25, v9, v13
	v_add_f32_e32 v27, v11, v15
	v_sub_f32_e32 v29, v11, v15
	v_add_f32_e32 v80, v22, v26
	v_add_f32_e32 v81, v23, v27
	ds_write_b64 v223, v[80:81] offset:32768
	v_sub_f32_e32 v242, v22, v26
	v_sub_f32_e32 v243, v23, v27
	v_add_f32_e32 v244, v24, v29
	v_sub_f32_e32 v245, v25, v28
	v_sub_f32_e32 v246, v24, v29
	v_add_f32_e32 v247, v25, v28
	v_mul_f32_e32 v227, v245, v17
	v_fma_f32 v82, v244, v16, -v227
	v_mul_f32_e32 v227, v245, v16
	v_fma_f32 v83, v244, v17, v227
	ds_write_b64 v223, v[82:83] offset:40960
	v_mul_f32_e32 v227, v243, v19
	v_fma_f32 v84, v242, v18, -v227
	v_mul_f32_e32 v227, v243, v18
	v_fma_f32 v85, v242, v19, v227
	ds_write_b64 v223, v[84:85] offset:49152
	v_mul_f32_e32 v227, v247, v21
	v_fma_f32 v236, v246, v20, -v227
	v_mul_f32_e32 v227, v247, v20
	v_fma_f32 v237, v246, v21, v227
	ds_write_b64 v223, v[236:237] offset:57344
	s_nop 0
	v_add_u32_e32 v226, 512, v154
	v_lshrrev_b32_e32 v224, 4, v226
	v_lshlrev_b32_e32 v224, 3, v224
	v_add_u32_e32 v224, 0x20800, v224
	v_and_b32_e32 v225, 15, v226
	v_lshlrev_b32_e32 v225, 5, v225
	v_add_u32_e32 v225, 0x20a00, v225
	ds_read_b64 v[238:239], v224
	ds_read_b64 v[240:241], v225
	s_waitcnt lgkmcnt(0)
; HD float2 cmul(float2 a, float2 b){ return make_float2(a.x*b.x - a.y*b.y, a.x*b.y + a.y*b.x); }
; HD float2 cmulc(float2 a, float2 b){ return make_float2(a.x*b.x + a.y*b.y, a.y*b.x - a.x*b.y); }
; template<bool INV, bool NOTW>
; HD void bf4c(float2* Z, int i0, int i1, int i2, int i3, float2 w1, float2 w2, float2 w3){
;   float2 a0=Z[i0], a1=Z[i1], a2=Z[i2], a3=Z[i3];
;   if (INV && !NOTW){ a1=cmulc(a1,w1); a2=cmulc(a2,w2); a3=cmulc(a3,w3); }
;   float2 s02=make_float2(a0.x+a2.x,a0.y+a2.y), d02=make_float2(a0.x-a2.x,a0.y-a2.y);
;   float2 s13=make_float2(a1.x+a3.x,a1.y+a3.y), d13=make_float2(a1.x-a3.x,a1.y-a3.y);
;   float2 y0=make_float2(s02.x+s13.x,s02.y+s13.y), y2=make_float2(s02.x-s13.x,s02.y-s13.y);
;   float2 ym=make_float2(d02.x+d13.y,d02.y-d13.x);
;   float2 yp=make_float2(d02.x-d13.y,d02.y+d13.x);
;   float2 y1, y3;
;   if (INV){ y1=yp; y3=ym; } else if (NOTW){ y1=ym; y3=yp; } else { y1=cmul(ym,w1); y2=cmul(y2,w2); y3=cmul(yp,w3); }
;   Z[i0]=y0; Z[i1]=y1; Z[i2]=y2; Z[i3]=y3;
; template<bool INV, int LQ, bool BARRIER=true>
; HD void fft_pass(float2* Z, const float2* twA, const float2* twB, int tid){
;     ...
;     _Pragma("unroll") for (int e=0;e<2;++e){ int j=tid+512*e; int k=j*tws;
;       float2 w1=cmul(twA[k>>6],twB[k&63]), w2=cmul(w1,w1), w3=cmul(w2,w1);
;       _Pragma("unroll") for (int ip=0;ip<4;++ip){ int base=ip*4096+j; bf4c<INV,false>(Z,base,base+q,base+2*q,base+3*q,w1,w2,w3); } }
	v_mul_f32_e32 v227, v239, v241
	v_fma_f32 v16, v238, v240, -v227
	v_mul_f32_e32 v227, v239, v240
	v_fma_f32 v17, v238, v241, v227
	v_mul_f32_e32 v227, v17, v17
	v_fma_f32 v18, v16, v16, -v227
	v_mul_f32_e32 v227, v17, v16
	v_fma_f32 v19, v16, v17, v227
	v_mul_f32_e32 v227, v19, v17
	v_fma_f32 v20, v18, v16, -v227
	v_mul_f32_e32 v227, v19, v16
	v_fma_f32 v21, v18, v17, v227
	ds_read_b64 v[0:1], v222 offset:4096
	ds_read_b64 v[2:3], v222 offset:12288
	ds_read_b64 v[4:5], v222 offset:20480
	ds_read_b64 v[6:7], v222 offset:28672
	ds_read_b64 v[8:9], v222 offset:36864
	ds_read_b64 v[10:11], v222 offset:45056
	ds_read_b64 v[12:13], v222 offset:53248
	ds_read_b64 v[14:15], v222 offset:61440
	s_waitcnt lgkmcnt(4)
	v_add_f32_e32 v22, v0, v4
	v_sub_f32_e32 v24, v0, v4
	v_add_f32_e32 v26, v2, v6
	v_sub_f32_e32 v28, v2, v6
	v_add_f32_e32 v23, v1, v5
	v_sub_f32_e32 v25, v1, v5
	v_add_f32_e32 v27, v3, v7
	v_sub_f32_e32 v29, v3, v7
	v_add_f32_e32 v80, v22, v26
	v_add_f32_e32 v81, v23, v27
	ds_write_b64 v222, v[80:81] offset:4096
	v_sub_f32_e32 v242, v22, v26
	v_sub_f32_e32 v243, v23, v27
	v_add_f32_e32 v244, v24, v29
	v_sub_f32_e32 v245, v25, v28
	v_sub_f32_e32 v246, v24, v29
	v_add_f32_e32 v247, v25, v28
	v_mul_f32_e32 v227, v245, v17
	v_fma_f32 v82, v244, v16, -v227
	v_mul_f32_e32 v227, v245, v16
	v_fma_f32 v83, v244, v17, v227
	ds_write_b64 v222, v[82:83] offset:12288
	v_mul_f32_e32 v227, v243, v19
	v_fma_f32 v84, v242, v18, -v227
	v_mul_f32_e32 v227, v243, v18
	v_fma_f32 v85, v242, v19, v227
	ds_write_b64 v222, v[84:85] offset:20480
	v_mul_f32_e32 v227, v247, v21
	v_fma_f32 v236, v246, v20, -v227
	v_mul_f32_e32 v227, v247, v20
	v_fma_f32 v237, v246, v21, v227
	ds_write_b64 v222, v[236:237] offset:28672
	ds_read_b64 v[0:1], v223 offset:4096
	ds_read_b64 v[2:3], v223 offset:12288
	ds_read_b64 v[4:5], v223 offset:20480
	ds_read_b64 v[6:7], v223 offset:28672
	s_waitcnt lgkmcnt(8)
	v_add_f32_e32 v22, v8, v12
	v_sub_f32_e32 v24, v8, v12
	v_add_f32_e32 v26, v10, v14
	v_sub_f32_e32 v28, v10, v14
	v_add_f32_e32 v23, v9, v13
	v_sub_f32_e32 v25, v9, v13
	v_add_f32_e32 v27, v11, v15
	v_sub_f32_e32 v29, v11, v15
	v_add_f32_e32 v80, v22, v26
	v_add_f32_e32 v81, v23, v27
	ds_write_b64 v222, v[80:81] offset:36864
	v_sub_f32_e32 v242, v22, v26
	v_sub_f32_e32 v243, v23, v27
	v_add_f32_e32 v244, v24, v29
	v_sub_f32_e32 v245, v25, v28
	v_sub_f32_e32 v246, v24, v29
	v_add_f32_e32 v247, v25, v28
	v_mul_f32_e32 v227, v245, v17
	v_fma_f32 v82, v244, v16, -v227
	v_mul_f32_e32 v227, v245, v16
	v_fma_f32 v83, v244, v17, v227
	ds_write_b64 v222, v[82:83] offset:45056
	v_mul_f32_e32 v227, v243, v19
	v_fma_f32 v84, v242, v18, -v227
	v_mul_f32_e32 v227, v243, v18
	v_fma_f32 v85, v242, v19, v227
	ds_write_b64 v222, v[84:85] offset:53248
	v_mul_f32_e32 v227, v247, v21
	v_fma_f32 v236, v246, v20, -v227
	v_mul_f32_e32 v227, v247, v20
	v_fma_f32 v237, v246, v21, v227
	ds_write_b64 v222, v[236:237] offset:61440
	ds_read_b64 v[8:9], v223 offset:36864
	ds_read_b64 v[10:11], v223 offset:45056
	ds_read_b64 v[12:13], v223 offset:53248
	ds_read_b64 v[14:15], v223 offset:61440
	s_waitcnt lgkmcnt(8)
	v_add_f32_e32 v22, v0, v4
	v_sub_f32_e32 v24, v0, v4
	v_add_f32_e32 v26, v2, v6
	v_sub_f32_e32 v28, v2, v6
	v_add_f32_e32 v23, v1, v5
	v_sub_f32_e32 v25, v1, v5
	v_add_f32_e32 v27, v3, v7
	v_sub_f32_e32 v29, v3, v7
	v_add_f32_e32 v80, v22, v26
	v_add_f32_e32 v81, v23, v27
	ds_write_b64 v223, v[80:81] offset:4096
	v_sub_f32_e32 v242, v22, v26
	v_sub_f32_e32 v243, v23, v27
	v_add_f32_e32 v244, v24, v29
	v_sub_f32_e32 v245, v25, v28
	v_sub_f32_e32 v246, v24, v29
	v_add_f32_e32 v247, v25, v28
	v_mul_f32_e32 v227, v245, v17
	v_fma_f32 v82, v244, v16, -v227
	v_mul_f32_e32 v227, v245, v16
	v_fma_f32 v83, v244, v17, v227
	ds_write_b64 v223, v[82:83] offset:12288
	v_mul_f32_e32 v227, v243, v19
	v_fma_f32 v84, v242, v18, -v227
	v_mul_f32_e32 v227, v243, v18
	v_fma_f32 v85, v242, v19, v227
	ds_write_b64 v223, v[84:85] offset:20480
	v_mul_f32_e32 v227, v247, v21
	v_fma_f32 v236, v246, v20, -v227
	v_mul_f32_e32 v227, v247, v20
	v_fma_f32 v237, v246, v21, v227
	ds_write_b64 v223, v[236:237] offset:28672
	s_waitcnt lgkmcnt(4)
	v_add_f32_e32 v22, v8, v12
	v_sub_f32_e32 v24, v8, v12
	v_add_f32_e32 v26, v10, v14
	v_sub_f32_e32 v28, v10, v14
	v_add_f32_e32 v23, v9, v13
	v_sub_f32_e32 v25, v9, v13
	v_add_f32_e32 v27, v11, v15
	v_sub_f32_e32 v29, v11, v15
	v_add_f32_e32 v80, v22, v26
	v_add_f32_e32 v81, v23, v27
	ds_write_b64 v223, v[80:81] offset:36864
	v_sub_f32_e32 v242, v22, v26
	v_sub_f32_e32 v243, v23, v27
	v_add_f32_e32 v244, v24, v29
	v_sub_f32_e32 v245, v25, v28
	v_sub_f32_e32 v246, v24, v29
	v_add_f32_e32 v247, v25, v28
	v_mul_f32_e32 v227, v245, v17
	v_fma_f32 v82, v244, v16, -v227
	v_mul_f32_e32 v227, v245, v16
	v_fma_f32 v83, v244, v17, v227
	ds_write_b64 v223, v[82:83] offset:45056
	v_mul_f32_e32 v227, v243, v19
	v_fma_f32 v84, v242, v18, -v227
	v_mul_f32_e32 v227, v243, v18
	v_fma_f32 v85, v242, v19, v227
	ds_write_b64 v223, v[84:85] offset:53248
	v_mul_f32_e32 v227, v247, v21
	v_fma_f32 v236, v246, v20, -v227
	v_mul_f32_e32 v227, v247, v20
	v_fma_f32 v237, v246, v21, v227
	ds_write_b64 v223, v[236:237] offset:61440
	s_waitcnt lgkmcnt(0)
	s_barrier
; HD float2 cmul(float2 a, float2 b){ return make_float2(a.x*b.x - a.y*b.y, a.x*b.y + a.y*b.x); }
; HD float2 cmulc(float2 a, float2 b){ return make_float2(a.x*b.x + a.y*b.y, a.y*b.x - a.x*b.y); }
; template<bool INV, bool NOTW>
; HD void bf4c(float2* Z, int i0, int i1, int i2, int i3, float2 w1, float2 w2, float2 w3){
;   float2 a0=Z[i0], a1=Z[i1], a2=Z[i2], a3=Z[i3];
;   if (INV && !NOTW){ a1=cmulc(a1,w1); a2=cmulc(a2,w2); a3=cmulc(a3,w3); }
;   float2 s02=make_float2(a0.x+a2.x,a0.y+a2.y), d02=make_float2(a0.x-a2.x,a0.y-a2.y);
;   float2 s13=make_float2(a1.x+a3.x,a1.y+a3.y), d13=make_float2(a1.x-a3.x,a1.y-a3.y);
;   float2 y0=make_float2(s02.x+s13.x,s02.y+s13.y), y2=make_float2(s02.x-s13.x,s02.y-s13.y);
;   float2 ym=make_float2(d02.x+d13.y,d02.y-d13.x);
;   float2 yp=make_float2(d02.x-d13.y,d02.y+d13.x);
;   float2 y1, y3;
;   if (INV){ y1=yp; y3=ym; } else if (NOTW){ y1=ym; y3=yp; } else { y1=cmul(ym,w1); y2=cmul(y2,w2); y3=cmul(yp,w3); }
;   Z[i0]=y0; Z[i1]=y1; Z[i2]=y2; Z[i3]=y3;
; template<bool INV, int LQ, bool BARRIER=true>
; HD void fft_pass(float2* Z, const float2* twA, const float2* twB, int tid){
;     ...
;     int j=tid&(q-1); int base0=((tid>>LQ)<<(LQ+2))+j;
;     float2 w1=make_float2(1.f,0.f), w2=w1, w3=w1;
;     if (LQ>0){ int k=j*tws; w1=cmul(twA[k>>6],twB[k&63]); w2=cmul(w1,w1); w3=cmul(w2,w1); }
;     _Pragma("unroll") for (int i=0;i<8;++i){ int base=base0+i*2048; bf4c<INV,(LQ==0)>(Z,base,base+q,base+2*q,base+3*q,w1,w2,w3); }
;   }
;   if (BARRIER) __syncthreads(); else asm volatile("s_waitcnt lgkmcnt(0)" ::: "memory");
	v_and_b32_e32 v226, 255, v154
	v_lshrrev_b32_e32 v224, 2, v226
	v_lshlrev_b32_e32 v224, 3, v224
	v_add_u32_e32 v224, 0x20800, v224
	v_and_b32_e32 v225, 3, v226
	v_lshlrev_b32_e32 v225, 7, v225
	v_add_u32_e32 v225, 0x20a00, v225
	ds_read_b64 v[238:239], v224
	ds_read_b64 v[240:241], v225
	s_waitcnt lgkmcnt(0)
	v_mul_f32_e32 v227, v239, v241
	v_fma_f32 v16, v238, v240, -v227
	v_mul_f32_e32 v227, v239, v240
	v_fma_f32 v17, v238, v241, v227
	v_mul_f32_e32 v227, v17, v17
	v_fma_f32 v18, v16, v16, -v227
	v_mul_f32_e32 v227, v17, v16
	v_fma_f32 v19, v16, v17, v227
	v_mul_f32_e32 v227, v19, v17
	v_fma_f32 v20, v18, v16, -v227
	v_mul_f32_e32 v227, v19, v16
	v_fma_f32 v21, v18, v17, v227
	v_lshrrev_b32_e32 v222, 8, v154
	v_lshlrev_b32_e32 v222, 10, v222
	v_add_u32_e32 v222, v222, v226
	v_lshlrev_b32_e32 v222, 3, v222
	v_add_u32_e32 v223, 0x10000, v222
	ds_read_b64 v[0:1], v222 offset:0
	ds_read_b64 v[2:3], v222 offset:2048
	ds_read_b64 v[4:5], v222 offset:4096
	ds_read_b64 v[6:7], v222 offset:6144
	ds_read_b64 v[8:9], v222 offset:16384
	ds_read_b64 v[10:11], v222 offset:18432
	ds_read_b64 v[12:13], v222 offset:20480
	ds_read_b64 v[14:15], v222 offset:22528
	s_waitcnt lgkmcnt(4)
	v_add_f32_e32 v22, v0, v4
	v_sub_f32_e32 v24, v0, v4
	v_add_f32_e32 v26, v2, v6
	v_sub_f32_e32 v28, v2, v6
	v_add_f32_e32 v23, v1, v5
	v_sub_f32_e32 v25, v1, v5
	v_add_f32_e32 v27, v3, v7
	v_sub_f32_e32 v29, v3, v7
	v_add_f32_e32 v80, v22, v26
	v_add_f32_e32 v81, v23, v27
	ds_write_b64 v222, v[80:81] offset:0
	v_sub_f32_e32 v242, v22, v26
	v_sub_f32_e32 v243, v23, v27
	v_add_f32_e32 v244, v24, v29
	v_sub_f32_e32 v245, v25, v28
	v_sub_f32_e32 v246, v24, v29
	v_add_f32_e32 v247, v25, v28
	v_mul_f32_e32 v227, v245, v17
	v_fma_f32 v82, v244, v16, -v227
	v_mul_f32_e32 v227, v245, v16
	v_fma_f32 v83, v244, v17, v227
	ds_write_b64 v222, v[82:83] offset:2048
	v_mul_f32_e32 v227, v243, v19
	v_fma_f32 v84, v242, v18, -v227
	v_mul_f32_e32 v227, v243, v18
	v_fma_f32 v85, v242, v19, v227
	ds_write_b64 v222, v[84:85] offset:4096
	v_mul_f32_e32 v227, v247, v21
	v_fma_f32 v236, v246, v20, -v227
	v_mul_f32_e32 v227, v247, v20
	v_fma_f32 v237, v246, v21, v227
	ds_write_b64 v222, v[236:237] offset:6144
	ds_read_b64 v[0:1], v222 offset:32768
	ds_read_b64 v[2:3], v222 offset:34816
	ds_read_b64 v[4:5], v222 offset:36864
	ds_read_b64 v[6:7], v222 offset:38912
	s_waitcnt lgkmcnt(8)
	v_add_f32_e32 v22, v8, v12
	v_sub_f32_e32 v24, v8, v12
	v_add_f32_e32 v26, v10, v14
	v_sub_f32_e32 v28, v10, v14
	v_add_f32_e32 v23, v9, v13
	v_sub_f32_e32 v25, v9, v13
	v_add_f32_e32 v27, v11, v15
	v_sub_f32_e32 v29, v11, v15
	v_add_f32_e32 v80, v22, v26
	v_add_f32_e32 v81, v23, v27
	ds_write_b64 v222, v[80:81] offset:16384
	v_sub_f32_e32 v242, v22, v26
	v_sub_f32_e32 v243, v23, v27
	v_add_f32_e32 v244, v24, v29
	v_sub_f32_e32 v245, v25, v28
	v_sub_f32_e32 v246, v24, v29
	v_add_f32_e32 v247, v25, v28
	v_mul_f32_e32 v227, v245, v17
	v_fma_f32 v82, v244, v16, -v227
	v_mul_f32_e32 v227, v245, v16
	v_fma_f32 v83, v244, v17, v227
	ds_write_b64 v222, v[82:83] offset:18432
	v_mul_f32_e32 v227, v243, v19
	v_fma_f32 v84, v242, v18, -v227
	v_mul_f32_e32 v227, v243, v18
	v_fma_f32 v85, v242, v19, v227
	ds_write_b64 v222, v[84:85] offset:20480
	v_mul_f32_e32 v227, v247, v21
	v_fma_f32 v236, v246, v20, -v227
	v_mul_f32_e32 v227, v247, v20
	v_fma_f32 v237, v246, v21, v227
	ds_write_b64 v222, v[236:237] offset:22528
	ds_read_b64 v[8:9], v222 offset:49152
	ds_read_b64 v[10:11], v222 offset:51200
	ds_read_b64 v[12:13], v222 offset:53248
	ds_read_b64 v[14:15], v222 offset:55296
	s_waitcnt lgkmcnt(8)
	v_add_f32_e32 v22, v0, v4
	v_sub_f32_e32 v24, v0, v4
	v_add_f32_e32 v26, v2, v6
	v_sub_f32_e32 v28, v2, v6
	v_add_f32_e32 v23, v1, v5
	v_sub_f32_e32 v25, v1, v5
	v_add_f32_e32 v27, v3, v7
	v_sub_f32_e32 v29, v3, v7
	v_add_f32_e32 v80, v22, v26
	v_add_f32_e32 v81, v23, v27
	ds_write_b64 v222, v[80:81] offset:32768
	v_sub_f32_e32 v242, v22, v26
	v_sub_f32_e32 v243, v23, v27
	v_add_f32_e32 v244, v24, v29
	v_sub_f32_e32 v245, v25, v28
	v_sub_f32_e32 v246, v24, v29
	v_add_f32_e32 v247, v25, v28
	v_mul_f32_e32 v227, v245, v17
	v_fma_f32 v82, v244, v16, -v227
	v_mul_f32_e32 v227, v245, v16
	v_fma_f32 v83, v244, v17, v227
	ds_write_b64 v222, v[82:83] offset:34816
	v_mul_f32_e32 v227, v243, v19
	v_fma_f32 v84, v242, v18, -v227
	v_mul_f32_e32 v227, v243, v18
	v_fma_f32 v85, v242, v19, v227
	ds_write_b64 v222, v[84:85] offset:36864
	v_mul_f32_e32 v227, v247, v21
	v_fma_f32 v236, v246, v20, -v227
	v_mul_f32_e32 v227, v247, v20
	v_fma_f32 v237, v246, v21, v227
	ds_write_b64 v222, v[236:237] offset:38912
	ds_read_b64 v[0:1], v223 offset:0
	ds_read_b64 v[2:3], v223 offset:2048
	ds_read_b64 v[4:5], v223 offset:4096
	ds_read_b64 v[6:7], v223 offset:6144
	s_waitcnt lgkmcnt(8)
	v_add_f32_e32 v22, v8, v12
	v_sub_f32_e32 v24, v8, v12
	v_add_f32_e32 v26, v10, v14
	v_sub_f32_e32 v28, v10, v14
	v_add_f32_e32 v23, v9, v13
	v_sub_f32_e32 v25, v9, v13
	v_add_f32_e32 v27, v11, v15
	v_sub_f32_e32 v29, v11, v15
	v_add_f32_e32 v80, v22, v26
	v_add_f32_e32 v81, v23, v27
	ds_write_b64 v222, v[80:81] offset:49152
	v_sub_f32_e32 v242, v22, v26
	v_sub_f32_e32 v243, v23, v27
	v_add_f32_e32 v244, v24, v29
	v_sub_f32_e32 v245, v25, v28
	v_sub_f32_e32 v246, v24, v29
	v_add_f32_e32 v247, v25, v28
	v_mul_f32_e32 v227, v245, v17
	v_fma_f32 v82, v244, v16, -v227
	v_mul_f32_e32 v227, v245, v16
	v_fma_f32 v83, v244, v17, v227
	ds_write_b64 v222, v[82:83] offset:51200
	v_mul_f32_e32 v227, v243, v19
	v_fma_f32 v84, v242, v18, -v227
	v_mul_f32_e32 v227, v243, v18
	v_fma_f32 v85, v242, v19, v227
	ds_write_b64 v222, v[84:85] offset:53248
	v_mul_f32_e32 v227, v247, v21
	v_fma_f32 v236, v246, v20, -v227
	v_mul_f32_e32 v227, v247, v20
	v_fma_f32 v237, v246, v21, v227
	ds_write_b64 v222, v[236:237] offset:55296
	ds_read_b64 v[8:9], v223 offset:16384
	ds_read_b64 v[10:11], v223 offset:18432
	ds_read_b64 v[12:13], v223 offset:20480
	ds_read_b64 v[14:15], v223 offset:22528
	s_waitcnt lgkmcnt(8)
; HD float2 cmul(float2 a, float2 b){ return make_float2(a.x*b.x - a.y*b.y, a.x*b.y + a.y*b.x); }
; HD float2 cmulc(float2 a, float2 b){ return make_float2(a.x*b.x + a.y*b.y, a.y*b.x - a.x*b.y); }
; template<bool INV, bool NOTW>
; HD void bf4c(float2* Z, int i0, int i1, int i2, int i3, float2 w1, float2 w2, float2 w3){
;   float2 a0=Z[i0], a1=Z[i1], a2=Z[i2], a3=Z[i3];
;   if (INV && !NOTW){ a1=cmulc(a1,w1); a2=cmulc(a2,w2); a3=cmulc(a3,w3); }
;   float2 s02=make_float2(a0.x+a2.x,a0.y+a2.y), d02=make_float2(a0.x-a2.x,a0.y-a2.y);
;   float2 s13=make_float2(a1.x+a3.x,a1.y+a3.y), d13=make_float2(a1.x-a3.x,a1.y-a3.y);
;   float2 y0=make_float2(s02.x+s13.x,s02.y+s13.y), y2=make_float2(s02.x-s13.x,s02.y-s13.y);
;   float2 ym=make_float2(d02.x+d13.y,d02.y-d13.x);
;   float2 yp=make_float2(d02.x-d13.y,d02.y+d13.x);
;   float2 y1, y3;
;   if (INV){ y1=yp; y3=ym; } else if (NOTW){ y1=ym; y3=yp; } else { y1=cmul(ym,w1); y2=cmul(y2,w2); y3=cmul(yp,w3); }
;   Z[i0]=y0; Z[i1]=y1; Z[i2]=y2; Z[i3]=y3;
; template<bool INV, int LQ, bool BARRIER=true>
; HD void fft_pass(float2* Z, const float2* twA, const float2* twB, int tid){
;     ...
;     int j=tid&(q-1); int base0=((tid>>LQ)<<(LQ+2))+j;
;     float2 w1=make_float2(1.f,0.f), w2=w1, w3=w1;
;     if (LQ>0){ int k=j*tws; w1=cmul(twA[k>>6],twB[k&63]); w2=cmul(w1,w1); w3=cmul(w2,w1); }
;     _Pragma("unroll") for (int i=0;i<8;++i){ int base=base0+i*2048; bf4c<INV,(LQ==0)>(Z,base,base+q,base+2*q,base+3*q,w1,w2,w3); }
;   }
;   if (BARRIER) __syncthreads(); else asm volatile("s_waitcnt lgkmcnt(0)" ::: "memory");
	v_add_f32_e32 v22, v0, v4
	v_sub_f32_e32 v24, v0, v4
	v_add_f32_e32 v26, v2, v6
	v_sub_f32_e32 v28, v2, v6
	v_add_f32_e32 v23, v1, v5
	v_sub_f32_e32 v25, v1, v5
	v_add_f32_e32 v27, v3, v7
	v_sub_f32_e32 v29, v3, v7
	v_add_f32_e32 v80, v22, v26
	v_add_f32_e32 v81, v23, v27
	ds_write_b64 v223, v[80:81] offset:0
	v_sub_f32_e32 v242, v22, v26
	v_sub_f32_e32 v243, v23, v27
	v_add_f32_e32 v244, v24, v29
	v_sub_f32_e32 v245, v25, v28
	v_sub_f32_e32 v246, v24, v29
	v_add_f32_e32 v247, v25, v28
	v_mul_f32_e32 v227, v245, v17
	v_fma_f32 v82, v244, v16, -v227
	v_mul_f32_e32 v227, v245, v16
	v_fma_f32 v83, v244, v17, v227
	ds_write_b64 v223, v[82:83] offset:2048
	v_mul_f32_e32 v227, v243, v19
	v_fma_f32 v84, v242, v18, -v227
	v_mul_f32_e32 v227, v243, v18
	v_fma_f32 v85, v242, v19, v227
	ds_write_b64 v223, v[84:85] offset:4096
	v_mul_f32_e32 v227, v247, v21
	v_fma_f32 v236, v246, v20, -v227
	v_mul_f32_e32 v227, v247, v20
	v_fma_f32 v237, v246, v21, v227
	ds_write_b64 v223, v[236:237] offset:6144
	ds_read_b64 v[0:1], v223 offset:32768
	ds_read_b64 v[2:3], v223 offset:34816
	ds_read_b64 v[4:5], v223 offset:36864
	ds_read_b64 v[6:7], v223 offset:38912
	s_waitcnt lgkmcnt(8)
	v_add_f32_e32 v22, v8, v12
	v_sub_f32_e32 v24, v8, v12
	v_add_f32_e32 v26, v10, v14
	v_sub_f32_e32 v28, v10, v14
	v_add_f32_e32 v23, v9, v13
	v_sub_f32_e32 v25, v9, v13
	v_add_f32_e32 v27, v11, v15
	v_sub_f32_e32 v29, v11, v15
	v_add_f32_e32 v80, v22, v26
	v_add_f32_e32 v81, v23, v27
	ds_write_b64 v223, v[80:81] offset:16384
	v_sub_f32_e32 v242, v22, v26
	v_sub_f32_e32 v243, v23, v27
	v_add_f32_e32 v244, v24, v29
	v_sub_f32_e32 v245, v25, v28
	v_sub_f32_e32 v246, v24, v29
	v_add_f32_e32 v247, v25, v28
	v_mul_f32_e32 v227, v245, v17
	v_fma_f32 v82, v244, v16, -v227
	v_mul_f32_e32 v227, v245, v16
	v_fma_f32 v83, v244, v17, v227
	ds_write_b64 v223, v[82:83] offset:18432
	v_mul_f32_e32 v227, v243, v19
	v_fma_f32 v84, v242, v18, -v227
	v_mul_f32_e32 v227, v243, v18
	v_fma_f32 v85, v242, v19, v227
	ds_write_b64 v223, v[84:85] offset:20480
	v_mul_f32_e32 v227, v247, v21
	v_fma_f32 v236, v246, v20, -v227
	v_mul_f32_e32 v227, v247, v20
	v_fma_f32 v237, v246, v21, v227
	ds_write_b64 v223, v[236:237] offset:22528
	ds_read_b64 v[8:9], v223 offset:49152
	ds_read_b64 v[10:11], v223 offset:51200
	ds_read_b64 v[12:13], v223 offset:53248
	ds_read_b64 v[14:15], v223 offset:55296
	s_waitcnt lgkmcnt(8)
	v_add_f32_e32 v22, v0, v4
	v_sub_f32_e32 v24, v0, v4
	v_add_f32_e32 v26, v2, v6
	v_sub_f32_e32 v28, v2, v6
	v_add_f32_e32 v23, v1, v5
	v_sub_f32_e32 v25, v1, v5
	v_add_f32_e32 v27, v3, v7
	v_sub_f32_e32 v29, v3, v7
	v_add_f32_e32 v80, v22, v26
	v_add_f32_e32 v81, v23, v27
	ds_write_b64 v223, v[80:81] offset:32768
	v_sub_f32_e32 v242, v22, v26
	v_sub_f32_e32 v243, v23, v27
	v_add_f32_e32 v244, v24, v29
	v_sub_f32_e32 v245, v25, v28
	v_sub_f32_e32 v246, v24, v29
	v_add_f32_e32 v247, v25, v28
	v_mul_f32_e32 v227, v245, v17
	v_fma_f32 v82, v244, v16, -v227
	v_mul_f32_e32 v227, v245, v16
	v_fma_f32 v83, v244, v17, v227
	ds_write_b64 v223, v[82:83] offset:34816
	v_mul_f32_e32 v227, v243, v19
	v_fma_f32 v84, v242, v18, -v227
	v_mul_f32_e32 v227, v243, v18
	v_fma_f32 v85, v242, v19, v227
	ds_write_b64 v223, v[84:85] offset:36864
	v_mul_f32_e32 v227, v247, v21
	v_fma_f32 v236, v246, v20, -v227
	v_mul_f32_e32 v227, v247, v20
	v_fma_f32 v237, v246, v21, v227
	ds_write_b64 v223, v[236:237] offset:38912
	s_waitcnt lgkmcnt(4)
	v_add_f32_e32 v22, v8, v12
	v_sub_f32_e32 v24, v8, v12
	v_add_f32_e32 v26, v10, v14
	v_sub_f32_e32 v28, v10, v14
	v_add_f32_e32 v23, v9, v13
	v_sub_f32_e32 v25, v9, v13
	v_add_f32_e32 v27, v11, v15
	v_sub_f32_e32 v29, v11, v15
	v_add_f32_e32 v80, v22, v26
	v_add_f32_e32 v81, v23, v27
	ds_write_b64 v223, v[80:81] offset:49152
	v_sub_f32_e32 v242, v22, v26
	v_sub_f32_e32 v243, v23, v27
	v_add_f32_e32 v244, v24, v29
	v_sub_f32_e32 v245, v25, v28
	v_sub_f32_e32 v246, v24, v29
	v_add_f32_e32 v247, v25, v28
	v_mul_f32_e32 v227, v245, v17
	v_fma_f32 v82, v244, v16, -v227
	v_mul_f32_e32 v227, v245, v16
	v_fma_f32 v83, v244, v17, v227
	ds_write_b64 v223, v[82:83] offset:51200
	v_mul_f32_e32 v227, v243, v19
	v_fma_f32 v84, v242, v18, -v227
	v_mul_f32_e32 v227, v243, v18
	v_fma_f32 v85, v242, v19, v227
	ds_write_b64 v223, v[84:85] offset:53248
	v_mul_f32_e32 v227, v247, v21
	v_fma_f32 v236, v246, v20, -v227
	v_mul_f32_e32 v227, v247, v20
	v_fma_f32 v237, v246, v21, v227
	ds_write_b64 v223, v[236:237] offset:55296
	s_waitcnt lgkmcnt(0)
	s_barrier
; HD float2 cmul(float2 a, float2 b){ return make_float2(a.x*b.x - a.y*b.y, a.x*b.y + a.y*b.x); }
; HD float2 cmulc(float2 a, float2 b){ return make_float2(a.x*b.x + a.y*b.y, a.y*b.x - a.x*b.y); }
; template<bool INV, bool NOTW>
; HD void bf4c(float2* Z, int i0, int i1, int i2, int i3, float2 w1, float2 w2, float2 w3){
;   float2 a0=Z[i0], a1=Z[i1], a2=Z[i2], a3=Z[i3];
;   if (INV && !NOTW){ a1=cmulc(a1,w1); a2=cmulc(a2,w2); a3=cmulc(a3,w3); }
;   float2 s02=make_float2(a0.x+a2.x,a0.y+a2.y), d02=make_float2(a0.x-a2.x,a0.y-a2.y);
;   float2 s13=make_float2(a1.x+a3.x,a1.y+a3.y), d13=make_float2(a1.x-a3.x,a1.y-a3.y);
;   float2 y0=make_float2(s02.x+s13.x,s02.y+s13.y), y2=make_float2(s02.x-s13.x,s02.y-s13.y);
;   float2 ym=make_float2(d02.x+d13.y,d02.y-d13.x);
;   float2 yp=make_float2(d02.x-d13.y,d02.y+d13.x);
;   float2 y1, y3;
;   if (INV){ y1=yp; y3=ym; } else if (NOTW){ y1=ym; y3=yp; } else { y1=cmul(ym,w1); y2=cmul(y2,w2); y3=cmul(yp,w3); }
;   Z[i0]=y0; Z[i1]=y1; Z[i2]=y2; Z[i3]=y3;
; template<bool INV, int LQ, bool BARRIER=true>
; HD void fft_pass(float2* Z, const float2* twA, const float2* twB, int tid){
;     ...
;     int j=tid&(q-1); int base0=((tid>>LQ)<<(LQ+2))+j;
;     float2 w1=make_float2(1.f,0.f), w2=w1, w3=w1;
;     if (LQ>0){ int k=j*tws; w1=cmul(twA[k>>6],twB[k&63]); w2=cmul(w1,w1); w3=cmul(w2,w1); }
;     _Pragma("unroll") for (int i=0;i<8;++i){ int base=base0+i*2048; bf4c<INV,(LQ==0)>(Z,base,base+q,base+2*q,base+3*q,w1,w2,w3); }
;   }
;   if (BARRIER) __syncthreads(); else asm volatile("s_waitcnt lgkmcnt(0)" ::: "memory");
	v_and_b32_e32 v226, 63, v154
	v_lshlrev_b32_e32 v224, 3, v226
	v_add_u32_e32 v224, 0x20800, v224
	v_mov_b32_e32 v225, 0x20a00
	ds_read_b64 v[238:239], v224
	ds_read_b64 v[240:241], v225
	s_waitcnt lgkmcnt(0)
	v_mul_f32_e32 v227, v239, v241
	v_fma_f32 v16, v238, v240, -v227
	v_mul_f32_e32 v227, v239, v240
	v_fma_f32 v17, v238, v241, v227
	v_mul_f32_e32 v227, v17, v17
	v_fma_f32 v18, v16, v16, -v227
	v_mul_f32_e32 v227, v17, v16
	v_fma_f32 v19, v16, v17, v227
	v_mul_f32_e32 v227, v19, v17
	v_fma_f32 v20, v18, v16, -v227
	v_mul_f32_e32 v227, v19, v16
	v_fma_f32 v21, v18, v17, v227
	v_lshrrev_b32_e32 v222, 6, v154
	v_lshlrev_b32_e32 v222, 8, v222
	v_add_u32_e32 v222, v222, v226
	v_lshlrev_b32_e32 v222, 3, v222
	v_add_u32_e32 v223, 0x10000, v222
	ds_read_b64 v[0:1], v222 offset:0
	ds_read_b64 v[2:3], v222 offset:512
	ds_read_b64 v[4:5], v222 offset:1024
	ds_read_b64 v[6:7], v222 offset:1536
	ds_read_b64 v[8:9], v222 offset:16384
	ds_read_b64 v[10:11], v222 offset:16896
	ds_read_b64 v[12:13], v222 offset:17408
	ds_read_b64 v[14:15], v222 offset:17920
	s_waitcnt lgkmcnt(4)
	v_add_f32_e32 v22, v0, v4
	v_sub_f32_e32 v24, v0, v4
	v_add_f32_e32 v26, v2, v6
	v_sub_f32_e32 v28, v2, v6
	v_add_f32_e32 v23, v1, v5
	v_sub_f32_e32 v25, v1, v5
	v_add_f32_e32 v27, v3, v7
	v_sub_f32_e32 v29, v3, v7
	v_add_f32_e32 v80, v22, v26
	v_add_f32_e32 v81, v23, v27
	ds_write_b64 v222, v[80:81] offset:0
	v_sub_f32_e32 v242, v22, v26
	v_sub_f32_e32 v243, v23, v27
	v_add_f32_e32 v244, v24, v29
	v_sub_f32_e32 v245, v25, v28
	v_sub_f32_e32 v246, v24, v29
	v_add_f32_e32 v247, v25, v28
	v_mul_f32_e32 v227, v245, v17
	v_fma_f32 v82, v244, v16, -v227
	v_mul_f32_e32 v227, v245, v16
	v_fma_f32 v83, v244, v17, v227
	ds_write_b64 v222, v[82:83] offset:512
	v_mul_f32_e32 v227, v243, v19
	v_fma_f32 v84, v242, v18, -v227
	v_mul_f32_e32 v227, v243, v18
	v_fma_f32 v85, v242, v19, v227
	ds_write_b64 v222, v[84:85] offset:1024
	v_mul_f32_e32 v227, v247, v21
	v_fma_f32 v236, v246, v20, -v227
	v_mul_f32_e32 v227, v247, v20
	v_fma_f32 v237, v246, v21, v227
	ds_write_b64 v222, v[236:237] offset:1536
	ds_read_b64 v[0:1], v222 offset:32768
	ds_read_b64 v[2:3], v222 offset:33280
	ds_read_b64 v[4:5], v222 offset:33792
	ds_read_b64 v[6:7], v222 offset:34304
	s_waitcnt lgkmcnt(8)
	v_add_f32_e32 v22, v8, v12
	v_sub_f32_e32 v24, v8, v12
	v_add_f32_e32 v26, v10, v14
	v_sub_f32_e32 v28, v10, v14
	v_add_f32_e32 v23, v9, v13
	v_sub_f32_e32 v25, v9, v13
	v_add_f32_e32 v27, v11, v15
	v_sub_f32_e32 v29, v11, v15
	v_add_f32_e32 v80, v22, v26
	v_add_f32_e32 v81, v23, v27
	ds_write_b64 v222, v[80:81] offset:16384
	v_sub_f32_e32 v242, v22, v26
	v_sub_f32_e32 v243, v23, v27
	v_add_f32_e32 v244, v24, v29
	v_sub_f32_e32 v245, v25, v28
	v_sub_f32_e32 v246, v24, v29
	v_add_f32_e32 v247, v25, v28
	v_mul_f32_e32 v227, v245, v17
	v_fma_f32 v82, v244, v16, -v227
	v_mul_f32_e32 v227, v245, v16
	v_fma_f32 v83, v244, v17, v227
	ds_write_b64 v222, v[82:83] offset:16896
	v_mul_f32_e32 v227, v243, v19
	v_fma_f32 v84, v242, v18, -v227
	v_mul_f32_e32 v227, v243, v18
	v_fma_f32 v85, v242, v19, v227
	ds_write_b64 v222, v[84:85] offset:17408
	v_mul_f32_e32 v227, v247, v21
	v_fma_f32 v236, v246, v20, -v227
	v_mul_f32_e32 v227, v247, v20
	v_fma_f32 v237, v246, v21, v227
	ds_write_b64 v222, v[236:237] offset:17920
	ds_read_b64 v[8:9], v222 offset:49152
	ds_read_b64 v[10:11], v222 offset:49664
	ds_read_b64 v[12:13], v222 offset:50176
	ds_read_b64 v[14:15], v222 offset:50688
	s_waitcnt lgkmcnt(8)
	v_add_f32_e32 v22, v0, v4
	v_sub_f32_e32 v24, v0, v4
	v_add_f32_e32 v26, v2, v6
	v_sub_f32_e32 v28, v2, v6
	v_add_f32_e32 v23, v1, v5
	v_sub_f32_e32 v25, v1, v5
	v_add_f32_e32 v27, v3, v7
	v_sub_f32_e32 v29, v3, v7
	v_add_f32_e32 v80, v22, v26
	v_add_f32_e32 v81, v23, v27
	ds_write_b64 v222, v[80:81] offset:32768
	v_sub_f32_e32 v242, v22, v26
	v_sub_f32_e32 v243, v23, v27
	v_add_f32_e32 v244, v24, v29
	v_sub_f32_e32 v245, v25, v28
	v_sub_f32_e32 v246, v24, v29
	v_add_f32_e32 v247, v25, v28
	v_mul_f32_e32 v227, v245, v17
	v_fma_f32 v82, v244, v16, -v227
	v_mul_f32_e32 v227, v245, v16
	v_fma_f32 v83, v244, v17, v227
	ds_write_b64 v222, v[82:83] offset:33280
	v_mul_f32_e32 v227, v243, v19
	v_fma_f32 v84, v242, v18, -v227
	v_mul_f32_e32 v227, v243, v18
	v_fma_f32 v85, v242, v19, v227
	ds_write_b64 v222, v[84:85] offset:33792
	v_mul_f32_e32 v227, v247, v21
	v_fma_f32 v236, v246, v20, -v227
	v_mul_f32_e32 v227, v247, v20
	v_fma_f32 v237, v246, v21, v227
	ds_write_b64 v222, v[236:237] offset:34304
	ds_read_b64 v[0:1], v223 offset:0
	ds_read_b64 v[2:3], v223 offset:512
	ds_read_b64 v[4:5], v223 offset:1024
	ds_read_b64 v[6:7], v223 offset:1536
	s_waitcnt lgkmcnt(8)
	v_add_f32_e32 v22, v8, v12
	v_sub_f32_e32 v24, v8, v12
	v_add_f32_e32 v26, v10, v14
	v_sub_f32_e32 v28, v10, v14
	v_add_f32_e32 v23, v9, v13
	v_sub_f32_e32 v25, v9, v13
	v_add_f32_e32 v27, v11, v15
	v_sub_f32_e32 v29, v11, v15
	v_add_f32_e32 v80, v22, v26
	v_add_f32_e32 v81, v23, v27
	ds_write_b64 v222, v[80:81] offset:49152
	v_sub_f32_e32 v242, v22, v26
	v_sub_f32_e32 v243, v23, v27
	v_add_f32_e32 v244, v24, v29
	v_sub_f32_e32 v245, v25, v28
	v_sub_f32_e32 v246, v24, v29
	v_add_f32_e32 v247, v25, v28
	v_mul_f32_e32 v227, v245, v17
	v_fma_f32 v82, v244, v16, -v227
	v_mul_f32_e32 v227, v245, v16
	v_fma_f32 v83, v244, v17, v227
	ds_write_b64 v222, v[82:83] offset:49664
	v_mul_f32_e32 v227, v243, v19
	v_fma_f32 v84, v242, v18, -v227
	v_mul_f32_e32 v227, v243, v18
	v_fma_f32 v85, v242, v19, v227
	ds_write_b64 v222, v[84:85] offset:50176
	v_mul_f32_e32 v227, v247, v21
	v_fma_f32 v236, v246, v20, -v227
	v_mul_f32_e32 v227, v247, v20
	v_fma_f32 v237, v246, v21, v227
	ds_write_b64 v222, v[236:237] offset:50688
	ds_read_b64 v[8:9], v223 offset:16384
	ds_read_b64 v[10:11], v223 offset:16896
	ds_read_b64 v[12:13], v223 offset:17408
	ds_read_b64 v[14:15], v223 offset:17920
	s_waitcnt lgkmcnt(8)
; HD float2 cmul(float2 a, float2 b){ return make_float2(a.x*b.x - a.y*b.y, a.x*b.y + a.y*b.x); }
; HD float2 cmulc(float2 a, float2 b){ return make_float2(a.x*b.x + a.y*b.y, a.y*b.x - a.x*b.y); }
; template<bool INV, bool NOTW>
; HD void bf4c(float2* Z, int i0, int i1, int i2, int i3, float2 w1, float2 w2, float2 w3){
;   float2 a0=Z[i0], a1=Z[i1], a2=Z[i2], a3=Z[i3];
;   if (INV && !NOTW){ a1=cmulc(a1,w1); a2=cmulc(a2,w2); a3=cmulc(a3,w3); }
;   float2 s02=make_float2(a0.x+a2.x,a0.y+a2.y), d02=make_float2(a0.x-a2.x,a0.y-a2.y);
;   float2 s13=make_float2(a1.x+a3.x,a1.y+a3.y), d13=make_float2(a1.x-a3.x,a1.y-a3.y);
;   float2 y0=make_float2(s02.x+s13.x,s02.y+s13.y), y2=make_float2(s02.x-s13.x,s02.y-s13.y);
;   float2 ym=make_float2(d02.x+d13.y,d02.y-d13.x);
;   float2 yp=make_float2(d02.x-d13.y,d02.y+d13.x);
;   float2 y1, y3;
;   if (INV){ y1=yp; y3=ym; } else if (NOTW){ y1=ym; y3=yp; } else { y1=cmul(ym,w1); y2=cmul(y2,w2); y3=cmul(yp,w3); }
;   Z[i0]=y0; Z[i1]=y1; Z[i2]=y2; Z[i3]=y3;
; template<bool INV, int LQ, bool BARRIER=true>
; HD void fft_pass(float2* Z, const float2* twA, const float2* twB, int tid){
;     ...
;     int j=tid&(q-1); int base0=((tid>>LQ)<<(LQ+2))+j;
;     float2 w1=make_float2(1.f,0.f), w2=w1, w3=w1;
;     if (LQ>0){ int k=j*tws; w1=cmul(twA[k>>6],twB[k&63]); w2=cmul(w1,w1); w3=cmul(w2,w1); }
;     _Pragma("unroll") for (int i=0;i<8;++i){ int base=base0+i*2048; bf4c<INV,(LQ==0)>(Z,base,base+q,base+2*q,base+3*q,w1,w2,w3); }
;   }
;   if (BARRIER) __syncthreads(); else asm volatile("s_waitcnt lgkmcnt(0)" ::: "memory");
	v_add_f32_e32 v22, v0, v4
	v_sub_f32_e32 v24, v0, v4
	v_add_f32_e32 v26, v2, v6
	v_sub_f32_e32 v28, v2, v6
	v_add_f32_e32 v23, v1, v5
	v_sub_f32_e32 v25, v1, v5
	v_add_f32_e32 v27, v3, v7
	v_sub_f32_e32 v29, v3, v7
	v_add_f32_e32 v80, v22, v26
	v_add_f32_e32 v81, v23, v27
	ds_write_b64 v223, v[80:81] offset:0
	v_sub_f32_e32 v242, v22, v26
	v_sub_f32_e32 v243, v23, v27
	v_add_f32_e32 v244, v24, v29
	v_sub_f32_e32 v245, v25, v28
	v_sub_f32_e32 v246, v24, v29
	v_add_f32_e32 v247, v25, v28
	v_mul_f32_e32 v227, v245, v17
	v_fma_f32 v82, v244, v16, -v227
	v_mul_f32_e32 v227, v245, v16
	v_fma_f32 v83, v244, v17, v227
	ds_write_b64 v223, v[82:83] offset:512
	v_mul_f32_e32 v227, v243, v19
	v_fma_f32 v84, v242, v18, -v227
	v_mul_f32_e32 v227, v243, v18
	v_fma_f32 v85, v242, v19, v227
	ds_write_b64 v223, v[84:85] offset:1024
	v_mul_f32_e32 v227, v247, v21
	v_fma_f32 v236, v246, v20, -v227
	v_mul_f32_e32 v227, v247, v20
	v_fma_f32 v237, v246, v21, v227
	ds_write_b64 v223, v[236:237] offset:1536
	ds_read_b64 v[0:1], v223 offset:32768
	ds_read_b64 v[2:3], v223 offset:33280
	ds_read_b64 v[4:5], v223 offset:33792
	ds_read_b64 v[6:7], v223 offset:34304
	s_waitcnt lgkmcnt(8)
	v_add_f32_e32 v22, v8, v12
	v_sub_f32_e32 v24, v8, v12
	v_add_f32_e32 v26, v10, v14
	v_sub_f32_e32 v28, v10, v14
	v_add_f32_e32 v23, v9, v13
	v_sub_f32_e32 v25, v9, v13
	v_add_f32_e32 v27, v11, v15
	v_sub_f32_e32 v29, v11, v15
	v_add_f32_e32 v80, v22, v26
	v_add_f32_e32 v81, v23, v27
	ds_write_b64 v223, v[80:81] offset:16384
	v_sub_f32_e32 v242, v22, v26
	v_sub_f32_e32 v243, v23, v27
	v_add_f32_e32 v244, v24, v29
	v_sub_f32_e32 v245, v25, v28
	v_sub_f32_e32 v246, v24, v29
	v_add_f32_e32 v247, v25, v28
	v_mul_f32_e32 v227, v245, v17
	v_fma_f32 v82, v244, v16, -v227
	v_mul_f32_e32 v227, v245, v16
	v_fma_f32 v83, v244, v17, v227
	ds_write_b64 v223, v[82:83] offset:16896
	v_mul_f32_e32 v227, v243, v19
	v_fma_f32 v84, v242, v18, -v227
	v_mul_f32_e32 v227, v243, v18
	v_fma_f32 v85, v242, v19, v227
	ds_write_b64 v223, v[84:85] offset:17408
	v_mul_f32_e32 v227, v247, v21
	v_fma_f32 v236, v246, v20, -v227
	v_mul_f32_e32 v227, v247, v20
	v_fma_f32 v237, v246, v21, v227
	ds_write_b64 v223, v[236:237] offset:17920
	ds_read_b64 v[8:9], v223 offset:49152
	ds_read_b64 v[10:11], v223 offset:49664
	ds_read_b64 v[12:13], v223 offset:50176
	ds_read_b64 v[14:15], v223 offset:50688
	s_waitcnt lgkmcnt(8)
	v_add_f32_e32 v22, v0, v4
	v_sub_f32_e32 v24, v0, v4
	v_add_f32_e32 v26, v2, v6
	v_sub_f32_e32 v28, v2, v6
	v_add_f32_e32 v23, v1, v5
	v_sub_f32_e32 v25, v1, v5
	v_add_f32_e32 v27, v3, v7
	v_sub_f32_e32 v29, v3, v7
	v_add_f32_e32 v80, v22, v26
	v_add_f32_e32 v81, v23, v27
	ds_write_b64 v223, v[80:81] offset:32768
	v_sub_f32_e32 v242, v22, v26
	v_sub_f32_e32 v243, v23, v27
	v_add_f32_e32 v244, v24, v29
	v_sub_f32_e32 v245, v25, v28
	v_sub_f32_e32 v246, v24, v29
	v_add_f32_e32 v247, v25, v28
	v_mul_f32_e32 v227, v245, v17
	v_fma_f32 v82, v244, v16, -v227
	v_mul_f32_e32 v227, v245, v16
	v_fma_f32 v83, v244, v17, v227
	ds_write_b64 v223, v[82:83] offset:33280
	v_mul_f32_e32 v227, v243, v19
	v_fma_f32 v84, v242, v18, -v227
	v_mul_f32_e32 v227, v243, v18
	v_fma_f32 v85, v242, v19, v227
	ds_write_b64 v223, v[84:85] offset:33792
	v_mul_f32_e32 v227, v247, v21
	v_fma_f32 v236, v246, v20, -v227
	v_mul_f32_e32 v227, v247, v20
	v_fma_f32 v237, v246, v21, v227
	ds_write_b64 v223, v[236:237] offset:34304
	s_waitcnt lgkmcnt(4)
	v_add_f32_e32 v22, v8, v12
	v_sub_f32_e32 v24, v8, v12
	v_add_f32_e32 v26, v10, v14
	v_sub_f32_e32 v28, v10, v14
	v_add_f32_e32 v23, v9, v13
	v_sub_f32_e32 v25, v9, v13
	v_add_f32_e32 v27, v11, v15
	v_sub_f32_e32 v29, v11, v15
	v_add_f32_e32 v80, v22, v26
	v_add_f32_e32 v81, v23, v27
	ds_write_b64 v223, v[80:81] offset:49152
	v_sub_f32_e32 v242, v22, v26
	v_sub_f32_e32 v243, v23, v27
	v_add_f32_e32 v244, v24, v29
	v_sub_f32_e32 v245, v25, v28
	v_sub_f32_e32 v246, v24, v29
	v_add_f32_e32 v247, v25, v28
	v_mul_f32_e32 v227, v245, v17
	v_fma_f32 v82, v244, v16, -v227
	v_mul_f32_e32 v227, v245, v16
	v_fma_f32 v83, v244, v17, v227
	ds_write_b64 v223, v[82:83] offset:49664
	v_mul_f32_e32 v227, v243, v19
	v_fma_f32 v84, v242, v18, -v227
	v_mul_f32_e32 v227, v243, v18
	v_fma_f32 v85, v242, v19, v227
	ds_write_b64 v223, v[84:85] offset:50176
	v_mul_f32_e32 v227, v247, v21
	v_fma_f32 v236, v246, v20, -v227
	v_mul_f32_e32 v227, v247, v20
	v_fma_f32 v237, v246, v21, v227
	ds_write_b64 v223, v[236:237] offset:50688
	s_waitcnt lgkmcnt(0)
	v_and_b32_e32 v226, 15, v154
	v_lshlrev_b32_e32 v224, 5, v226
	v_add_u32_e32 v224, 0x20800, v224
	v_mov_b32_e32 v225, 0x20a00
	ds_read_b64 v[238:239], v224
	ds_read_b64 v[240:241], v225
	s_waitcnt lgkmcnt(0)
	v_mul_f32_e32 v227, v239, v241
	v_fma_f32 v16, v238, v240, -v227
	v_mul_f32_e32 v227, v239, v240
	v_fma_f32 v17, v238, v241, v227
	v_mul_f32_e32 v227, v17, v17
	v_fma_f32 v18, v16, v16, -v227
	v_mul_f32_e32 v227, v17, v16
	v_fma_f32 v19, v16, v17, v227
	v_mul_f32_e32 v227, v19, v17
	v_fma_f32 v20, v18, v16, -v227
	v_mul_f32_e32 v227, v19, v16
	v_fma_f32 v21, v18, v17, v227
	v_lshrrev_b32_e32 v222, 4, v154
	v_lshlrev_b32_e32 v222, 6, v222
	v_add_u32_e32 v222, v222, v226
	v_lshlrev_b32_e32 v222, 3, v222
	v_add_u32_e32 v223, 0x10000, v222
	ds_read_b64 v[0:1], v222 offset:0
	ds_read_b64 v[2:3], v222 offset:128
	ds_read_b64 v[4:5], v222 offset:256
	ds_read_b64 v[6:7], v222 offset:384
	ds_read_b64 v[8:9], v222 offset:16384
	ds_read_b64 v[10:11], v222 offset:16512
	ds_read_b64 v[12:13], v222 offset:16640
	ds_read_b64 v[14:15], v222 offset:16768
	s_waitcnt lgkmcnt(4)
; HD float2 cmul(float2 a, float2 b){ return make_float2(a.x*b.x - a.y*b.y, a.x*b.y + a.y*b.x); }
; HD float2 cmulc(float2 a, float2 b){ return make_float2(a.x*b.x + a.y*b.y, a.y*b.x - a.x*b.y); }
; template<bool INV, bool NOTW>
; HD void bf4c(float2* Z, int i0, int i1, int i2, int i3, float2 w1, float2 w2, float2 w3){
;   float2 a0=Z[i0], a1=Z[i1], a2=Z[i2], a3=Z[i3];
;   if (INV && !NOTW){ a1=cmulc(a1,w1); a2=cmulc(a2,w2); a3=cmulc(a3,w3); }
;   float2 s02=make_float2(a0.x+a2.x,a0.y+a2.y), d02=make_float2(a0.x-a2.x,a0.y-a2.y);
;   float2 s13=make_float2(a1.x+a3.x,a1.y+a3.y), d13=make_float2(a1.x-a3.x,a1.y-a3.y);
;   float2 y0=make_float2(s02.x+s13.x,s02.y+s13.y), y2=make_float2(s02.x-s13.x,s02.y-s13.y);
;   float2 ym=make_float2(d02.x+d13.y,d02.y-d13.x);
;   float2 yp=make_float2(d02.x-d13.y,d02.y+d13.x);
;   float2 y1, y3;
;   if (INV){ y1=yp; y3=ym; } else if (NOTW){ y1=ym; y3=yp; } else { y1=cmul(ym,w1); y2=cmul(y2,w2); y3=cmul(yp,w3); }
;   Z[i0]=y0; Z[i1]=y1; Z[i2]=y2; Z[i3]=y3;
; template<bool INV, int LQ, bool BARRIER=true>
; HD void fft_pass(float2* Z, const float2* twA, const float2* twB, int tid){
;     ...
;     int j=tid&(q-1); int base0=((tid>>LQ)<<(LQ+2))+j;
;     float2 w1=make_float2(1.f,0.f), w2=w1, w3=w1;
;     if (LQ>0){ int k=j*tws; w1=cmul(twA[k>>6],twB[k&63]); w2=cmul(w1,w1); w3=cmul(w2,w1); }
;     _Pragma("unroll") for (int i=0;i<8;++i){ int base=base0+i*2048; bf4c<INV,(LQ==0)>(Z,base,base+q,base+2*q,base+3*q,w1,w2,w3); }
;   }
;   if (BARRIER) __syncthreads(); else asm volatile("s_waitcnt lgkmcnt(0)" ::: "memory");
	v_add_f32_e32 v22, v0, v4
	v_sub_f32_e32 v24, v0, v4
	v_add_f32_e32 v26, v2, v6
	v_sub_f32_e32 v28, v2, v6
	v_add_f32_e32 v23, v1, v5
	v_sub_f32_e32 v25, v1, v5
	v_add_f32_e32 v27, v3, v7
	v_sub_f32_e32 v29, v3, v7
	v_add_f32_e32 v80, v22, v26
	v_add_f32_e32 v81, v23, v27
	ds_write_b64 v222, v[80:81] offset:0
	v_sub_f32_e32 v242, v22, v26
	v_sub_f32_e32 v243, v23, v27
	v_add_f32_e32 v244, v24, v29
	v_sub_f32_e32 v245, v25, v28
	v_sub_f32_e32 v246, v24, v29
	v_add_f32_e32 v247, v25, v28
	v_mul_f32_e32 v227, v245, v17
	v_fma_f32 v82, v244, v16, -v227
	v_mul_f32_e32 v227, v245, v16
	v_fma_f32 v83, v244, v17, v227
	ds_write_b64 v222, v[82:83] offset:128
	v_mul_f32_e32 v227, v243, v19
	v_fma_f32 v84, v242, v18, -v227
	v_mul_f32_e32 v227, v243, v18
	v_fma_f32 v85, v242, v19, v227
	ds_write_b64 v222, v[84:85] offset:256
	v_mul_f32_e32 v227, v247, v21
	v_fma_f32 v236, v246, v20, -v227
	v_mul_f32_e32 v227, v247, v20
	v_fma_f32 v237, v246, v21, v227
	ds_write_b64 v222, v[236:237] offset:384
	ds_read_b64 v[0:1], v222 offset:32768
	ds_read_b64 v[2:3], v222 offset:32896
	ds_read_b64 v[4:5], v222 offset:33024
	ds_read_b64 v[6:7], v222 offset:33152
	s_waitcnt lgkmcnt(8)
	v_add_f32_e32 v22, v8, v12
	v_sub_f32_e32 v24, v8, v12
	v_add_f32_e32 v26, v10, v14
	v_sub_f32_e32 v28, v10, v14
	v_add_f32_e32 v23, v9, v13
	v_sub_f32_e32 v25, v9, v13
	v_add_f32_e32 v27, v11, v15
	v_sub_f32_e32 v29, v11, v15
	v_add_f32_e32 v80, v22, v26
	v_add_f32_e32 v81, v23, v27
	ds_write_b64 v222, v[80:81] offset:16384
	v_sub_f32_e32 v242, v22, v26
	v_sub_f32_e32 v243, v23, v27
	v_add_f32_e32 v244, v24, v29
	v_sub_f32_e32 v245, v25, v28
	v_sub_f32_e32 v246, v24, v29
	v_add_f32_e32 v247, v25, v28
	v_mul_f32_e32 v227, v245, v17
	v_fma_f32 v82, v244, v16, -v227
	v_mul_f32_e32 v227, v245, v16
	v_fma_f32 v83, v244, v17, v227
	ds_write_b64 v222, v[82:83] offset:16512
	v_mul_f32_e32 v227, v243, v19
	v_fma_f32 v84, v242, v18, -v227
	v_mul_f32_e32 v227, v243, v18
	v_fma_f32 v85, v242, v19, v227
	ds_write_b64 v222, v[84:85] offset:16640
	v_mul_f32_e32 v227, v247, v21
	v_fma_f32 v236, v246, v20, -v227
	v_mul_f32_e32 v227, v247, v20
	v_fma_f32 v237, v246, v21, v227
	ds_write_b64 v222, v[236:237] offset:16768
	ds_read_b64 v[8:9], v222 offset:49152
	ds_read_b64 v[10:11], v222 offset:49280
	ds_read_b64 v[12:13], v222 offset:49408
	ds_read_b64 v[14:15], v222 offset:49536
	s_waitcnt lgkmcnt(8)
	v_add_f32_e32 v22, v0, v4
	v_sub_f32_e32 v24, v0, v4
	v_add_f32_e32 v26, v2, v6
	v_sub_f32_e32 v28, v2, v6
	v_add_f32_e32 v23, v1, v5
	v_sub_f32_e32 v25, v1, v5
	v_add_f32_e32 v27, v3, v7
	v_sub_f32_e32 v29, v3, v7
	v_add_f32_e32 v80, v22, v26
	v_add_f32_e32 v81, v23, v27
	ds_write_b64 v222, v[80:81] offset:32768
	v_sub_f32_e32 v242, v22, v26
	v_sub_f32_e32 v243, v23, v27
	v_add_f32_e32 v244, v24, v29
	v_sub_f32_e32 v245, v25, v28
	v_sub_f32_e32 v246, v24, v29
	v_add_f32_e32 v247, v25, v28
	v_mul_f32_e32 v227, v245, v17
	v_fma_f32 v82, v244, v16, -v227
	v_mul_f32_e32 v227, v245, v16
	v_fma_f32 v83, v244, v17, v227
	ds_write_b64 v222, v[82:83] offset:32896
	v_mul_f32_e32 v227, v243, v19
	v_fma_f32 v84, v242, v18, -v227
	v_mul_f32_e32 v227, v243, v18
	v_fma_f32 v85, v242, v19, v227
	ds_write_b64 v222, v[84:85] offset:33024
	v_mul_f32_e32 v227, v247, v21
	v_fma_f32 v236, v246, v20, -v227
	v_mul_f32_e32 v227, v247, v20
	v_fma_f32 v237, v246, v21, v227
	ds_write_b64 v222, v[236:237] offset:33152
	ds_read_b64 v[0:1], v223 offset:0
	ds_read_b64 v[2:3], v223 offset:128
	ds_read_b64 v[4:5], v223 offset:256
	ds_read_b64 v[6:7], v223 offset:384
	s_waitcnt lgkmcnt(8)
	v_add_f32_e32 v22, v8, v12
	v_sub_f32_e32 v24, v8, v12
	v_add_f32_e32 v26, v10, v14
	v_sub_f32_e32 v28, v10, v14
	v_add_f32_e32 v23, v9, v13
	v_sub_f32_e32 v25, v9, v13
	v_add_f32_e32 v27, v11, v15
	v_sub_f32_e32 v29, v11, v15
	v_add_f32_e32 v80, v22, v26
	v_add_f32_e32 v81, v23, v27
	ds_write_b64 v222, v[80:81] offset:49152
	v_sub_f32_e32 v242, v22, v26
	v_sub_f32_e32 v243, v23, v27
	v_add_f32_e32 v244, v24, v29
	v_sub_f32_e32 v245, v25, v28
	v_sub_f32_e32 v246, v24, v29
	v_add_f32_e32 v247, v25, v28
	v_mul_f32_e32 v227, v245, v17
	v_fma_f32 v82, v244, v16, -v227
	v_mul_f32_e32 v227, v245, v16
	v_fma_f32 v83, v244, v17, v227
	ds_write_b64 v222, v[82:83] offset:49280
	v_mul_f32_e32 v227, v243, v19
	v_fma_f32 v84, v242, v18, -v227
	v_mul_f32_e32 v227, v243, v18
	v_fma_f32 v85, v242, v19, v227
	ds_write_b64 v222, v[84:85] offset:49408
	v_mul_f32_e32 v227, v247, v21
	v_fma_f32 v236, v246, v20, -v227
	v_mul_f32_e32 v227, v247, v20
	v_fma_f32 v237, v246, v21, v227
	ds_write_b64 v222, v[236:237] offset:49536
	ds_read_b64 v[8:9], v223 offset:16384
	ds_read_b64 v[10:11], v223 offset:16512
	ds_read_b64 v[12:13], v223 offset:16640
	ds_read_b64 v[14:15], v223 offset:16768
	s_waitcnt lgkmcnt(8)
	v_add_f32_e32 v22, v0, v4
	v_sub_f32_e32 v24, v0, v4
	v_add_f32_e32 v26, v2, v6
	v_sub_f32_e32 v28, v2, v6
	v_add_f32_e32 v23, v1, v5
	v_sub_f32_e32 v25, v1, v5
	v_add_f32_e32 v27, v3, v7
	v_sub_f32_e32 v29, v3, v7
	v_add_f32_e32 v80, v22, v26
	v_add_f32_e32 v81, v23, v27
	ds_write_b64 v223, v[80:81] offset:0
	v_sub_f32_e32 v242, v22, v26
	v_sub_f32_e32 v243, v23, v27
	v_add_f32_e32 v244, v24, v29
	v_sub_f32_e32 v245, v25, v28
	v_sub_f32_e32 v246, v24, v29
	v_add_f32_e32 v247, v25, v28
	v_mul_f32_e32 v227, v245, v17
	v_fma_f32 v82, v244, v16, -v227
	v_mul_f32_e32 v227, v245, v16
	v_fma_f32 v83, v244, v17, v227
	ds_write_b64 v223, v[82:83] offset:128
	v_mul_f32_e32 v227, v243, v19
	v_fma_f32 v84, v242, v18, -v227
	v_mul_f32_e32 v227, v243, v18
	v_fma_f32 v85, v242, v19, v227
	ds_write_b64 v223, v[84:85] offset:256
	v_mul_f32_e32 v227, v247, v21
	v_fma_f32 v236, v246, v20, -v227
	v_mul_f32_e32 v227, v247, v20
	v_fma_f32 v237, v246, v21, v227
	ds_write_b64 v223, v[236:237] offset:384
	ds_read_b64 v[0:1], v223 offset:32768
	ds_read_b64 v[2:3], v223 offset:32896
	ds_read_b64 v[4:5], v223 offset:33024
	ds_read_b64 v[6:7], v223 offset:33152
	s_waitcnt lgkmcnt(8)
; HD float2 cmul(float2 a, float2 b){ return make_float2(a.x*b.x - a.y*b.y, a.x*b.y + a.y*b.x); }
; HD float2 cmulc(float2 a, float2 b){ return make_float2(a.x*b.x + a.y*b.y, a.y*b.x - a.x*b.y); }
; template<bool INV, bool NOTW>
; HD void bf4c(float2* Z, int i0, int i1, int i2, int i3, float2 w1, float2 w2, float2 w3){
;   float2 a0=Z[i0], a1=Z[i1], a2=Z[i2], a3=Z[i3];
;   if (INV && !NOTW){ a1=cmulc(a1,w1); a2=cmulc(a2,w2); a3=cmulc(a3,w3); }
;   float2 s02=make_float2(a0.x+a2.x,a0.y+a2.y), d02=make_float2(a0.x-a2.x,a0.y-a2.y);
;   float2 s13=make_float2(a1.x+a3.x,a1.y+a3.y), d13=make_float2(a1.x-a3.x,a1.y-a3.y);
;   float2 y0=make_float2(s02.x+s13.x,s02.y+s13.y), y2=make_float2(s02.x-s13.x,s02.y-s13.y);
;   float2 ym=make_float2(d02.x+d13.y,d02.y-d13.x);
;   float2 yp=make_float2(d02.x-d13.y,d02.y+d13.x);
;   float2 y1, y3;
;   if (INV){ y1=yp; y3=ym; } else if (NOTW){ y1=ym; y3=yp; } else { y1=cmul(ym,w1); y2=cmul(y2,w2); y3=cmul(yp,w3); }
;   Z[i0]=y0; Z[i1]=y1; Z[i2]=y2; Z[i3]=y3;
; template<bool INV, int LQ, bool BARRIER=true>
; HD void fft_pass(float2* Z, const float2* twA, const float2* twB, int tid){
;     ...
;     int j=tid&(q-1); int base0=((tid>>LQ)<<(LQ+2))+j;
;     float2 w1=make_float2(1.f,0.f), w2=w1, w3=w1;
;     if (LQ>0){ int k=j*tws; w1=cmul(twA[k>>6],twB[k&63]); w2=cmul(w1,w1); w3=cmul(w2,w1); }
;     _Pragma("unroll") for (int i=0;i<8;++i){ int base=base0+i*2048; bf4c<INV,(LQ==0)>(Z,base,base+q,base+2*q,base+3*q,w1,w2,w3); }
;   }
;   if (BARRIER) __syncthreads(); else asm volatile("s_waitcnt lgkmcnt(0)" ::: "memory");
	v_add_f32_e32 v22, v8, v12
	v_sub_f32_e32 v24, v8, v12
	v_add_f32_e32 v26, v10, v14
	v_sub_f32_e32 v28, v10, v14
	v_add_f32_e32 v23, v9, v13
	v_sub_f32_e32 v25, v9, v13
	v_add_f32_e32 v27, v11, v15
	v_sub_f32_e32 v29, v11, v15
	v_add_f32_e32 v80, v22, v26
	v_add_f32_e32 v81, v23, v27
	ds_write_b64 v223, v[80:81] offset:16384
	v_sub_f32_e32 v242, v22, v26
	v_sub_f32_e32 v243, v23, v27
	v_add_f32_e32 v244, v24, v29
	v_sub_f32_e32 v245, v25, v28
	v_sub_f32_e32 v246, v24, v29
	v_add_f32_e32 v247, v25, v28
	v_mul_f32_e32 v227, v245, v17
	v_fma_f32 v82, v244, v16, -v227
	v_mul_f32_e32 v227, v245, v16
	v_fma_f32 v83, v244, v17, v227
	ds_write_b64 v223, v[82:83] offset:16512
	v_mul_f32_e32 v227, v243, v19
	v_fma_f32 v84, v242, v18, -v227
	v_mul_f32_e32 v227, v243, v18
	v_fma_f32 v85, v242, v19, v227
	ds_write_b64 v223, v[84:85] offset:16640
	v_mul_f32_e32 v227, v247, v21
	v_fma_f32 v236, v246, v20, -v227
	v_mul_f32_e32 v227, v247, v20
	v_fma_f32 v237, v246, v21, v227
	ds_write_b64 v223, v[236:237] offset:16768
	ds_read_b64 v[8:9], v223 offset:49152
	ds_read_b64 v[10:11], v223 offset:49280
	ds_read_b64 v[12:13], v223 offset:49408
	ds_read_b64 v[14:15], v223 offset:49536
	s_waitcnt lgkmcnt(8)
	v_add_f32_e32 v22, v0, v4
	v_sub_f32_e32 v24, v0, v4
	v_add_f32_e32 v26, v2, v6
	v_sub_f32_e32 v28, v2, v6
	v_add_f32_e32 v23, v1, v5
	v_sub_f32_e32 v25, v1, v5
	v_add_f32_e32 v27, v3, v7
	v_sub_f32_e32 v29, v3, v7
	v_add_f32_e32 v80, v22, v26
	v_add_f32_e32 v81, v23, v27
	ds_write_b64 v223, v[80:81] offset:32768
	v_sub_f32_e32 v242, v22, v26
	v_sub_f32_e32 v243, v23, v27
	v_add_f32_e32 v244, v24, v29
	v_sub_f32_e32 v245, v25, v28
	v_sub_f32_e32 v246, v24, v29
	v_add_f32_e32 v247, v25, v28
	v_mul_f32_e32 v227, v245, v17
	v_fma_f32 v82, v244, v16, -v227
	v_mul_f32_e32 v227, v245, v16
	v_fma_f32 v83, v244, v17, v227
	ds_write_b64 v223, v[82:83] offset:32896
	v_mul_f32_e32 v227, v243, v19
	v_fma_f32 v84, v242, v18, -v227
	v_mul_f32_e32 v227, v243, v18
	v_fma_f32 v85, v242, v19, v227
	ds_write_b64 v223, v[84:85] offset:33024
	v_mul_f32_e32 v227, v247, v21
	v_fma_f32 v236, v246, v20, -v227
	v_mul_f32_e32 v227, v247, v20
	v_fma_f32 v237, v246, v21, v227
	ds_write_b64 v223, v[236:237] offset:33152
	s_waitcnt lgkmcnt(4)
	v_add_f32_e32 v22, v8, v12
	v_sub_f32_e32 v24, v8, v12
	v_add_f32_e32 v26, v10, v14
	v_sub_f32_e32 v28, v10, v14
	v_add_f32_e32 v23, v9, v13
	v_sub_f32_e32 v25, v9, v13
	v_add_f32_e32 v27, v11, v15
	v_sub_f32_e32 v29, v11, v15
	v_add_f32_e32 v80, v22, v26
	v_add_f32_e32 v81, v23, v27
	ds_write_b64 v223, v[80:81] offset:49152
	v_sub_f32_e32 v242, v22, v26
	v_sub_f32_e32 v243, v23, v27
	v_add_f32_e32 v244, v24, v29
	v_sub_f32_e32 v245, v25, v28
	v_sub_f32_e32 v246, v24, v29
	v_add_f32_e32 v247, v25, v28
	v_mul_f32_e32 v227, v245, v17
	v_fma_f32 v82, v244, v16, -v227
	v_mul_f32_e32 v227, v245, v16
	v_fma_f32 v83, v244, v17, v227
	ds_write_b64 v223, v[82:83] offset:49280
	v_mul_f32_e32 v227, v243, v19
	v_fma_f32 v84, v242, v18, -v227
	v_mul_f32_e32 v227, v243, v18
	v_fma_f32 v85, v242, v19, v227
	ds_write_b64 v223, v[84:85] offset:49408
	v_mul_f32_e32 v227, v247, v21
	v_fma_f32 v236, v246, v20, -v227
	v_mul_f32_e32 v227, v247, v20
	v_fma_f32 v237, v246, v21, v227
	ds_write_b64 v223, v[236:237] offset:49536
	s_waitcnt lgkmcnt(0)
	v_and_b32_e32 v226, 3, v154
	v_lshlrev_b32_e32 v224, 7, v226
	v_add_u32_e32 v224, 0x20800, v224
	v_mov_b32_e32 v225, 0x20a00
	ds_read_b64 v[238:239], v224
	ds_read_b64 v[240:241], v225
	s_waitcnt lgkmcnt(0)
	v_mul_f32_e32 v227, v239, v241
	v_fma_f32 v16, v238, v240, -v227
	v_mul_f32_e32 v227, v239, v240
	v_fma_f32 v17, v238, v241, v227
	v_mul_f32_e32 v227, v17, v17
	v_fma_f32 v18, v16, v16, -v227
	v_mul_f32_e32 v227, v17, v16
	v_fma_f32 v19, v16, v17, v227
	v_mul_f32_e32 v227, v19, v17
	v_fma_f32 v20, v18, v16, -v227
	v_mul_f32_e32 v227, v19, v16
	v_fma_f32 v21, v18, v17, v227
	v_lshrrev_b32_e32 v222, 2, v154
	v_lshlrev_b32_e32 v222, 4, v222
	v_add_u32_e32 v222, v222, v226
	v_lshlrev_b32_e32 v222, 3, v222
	v_add_u32_e32 v223, 0x10000, v222
	ds_read_b64 v[0:1], v222 offset:0
	ds_read_b64 v[2:3], v222 offset:32
	ds_read_b64 v[4:5], v222 offset:64
	ds_read_b64 v[6:7], v222 offset:96
	ds_read_b64 v[8:9], v222 offset:16384
	ds_read_b64 v[10:11], v222 offset:16416
	ds_read_b64 v[12:13], v222 offset:16448
	ds_read_b64 v[14:15], v222 offset:16480
	s_waitcnt lgkmcnt(4)
	v_add_f32_e32 v22, v0, v4
	v_sub_f32_e32 v24, v0, v4
	v_add_f32_e32 v26, v2, v6
	v_sub_f32_e32 v28, v2, v6
	v_add_f32_e32 v23, v1, v5
	v_sub_f32_e32 v25, v1, v5
	v_add_f32_e32 v27, v3, v7
	v_sub_f32_e32 v29, v3, v7
	v_add_f32_e32 v80, v22, v26
	v_add_f32_e32 v81, v23, v27
	ds_write_b64 v222, v[80:81] offset:0
	v_sub_f32_e32 v242, v22, v26
	v_sub_f32_e32 v243, v23, v27
	v_add_f32_e32 v244, v24, v29
	v_sub_f32_e32 v245, v25, v28
	v_sub_f32_e32 v246, v24, v29
	v_add_f32_e32 v247, v25, v28
	v_mul_f32_e32 v227, v245, v17
	v_fma_f32 v82, v244, v16, -v227
	v_mul_f32_e32 v227, v245, v16
	v_fma_f32 v83, v244, v17, v227
	ds_write_b64 v222, v[82:83] offset:32
	v_mul_f32_e32 v227, v243, v19
	v_fma_f32 v84, v242, v18, -v227
	v_mul_f32_e32 v227, v243, v18
	v_fma_f32 v85, v242, v19, v227
	ds_write_b64 v222, v[84:85] offset:64
	v_mul_f32_e32 v227, v247, v21
	v_fma_f32 v236, v246, v20, -v227
	v_mul_f32_e32 v227, v247, v20
	v_fma_f32 v237, v246, v21, v227
	ds_write_b64 v222, v[236:237] offset:96
	ds_read_b64 v[0:1], v222 offset:32768
	ds_read_b64 v[2:3], v222 offset:32800
	ds_read_b64 v[4:5], v222 offset:32832
	ds_read_b64 v[6:7], v222 offset:32864
	s_waitcnt lgkmcnt(8)
; HD float2 cmul(float2 a, float2 b){ return make_float2(a.x*b.x - a.y*b.y, a.x*b.y + a.y*b.x); }
; HD float2 cmulc(float2 a, float2 b){ return make_float2(a.x*b.x + a.y*b.y, a.y*b.x - a.x*b.y); }
; template<bool INV, bool NOTW>
; HD void bf4c(float2* Z, int i0, int i1, int i2, int i3, float2 w1, float2 w2, float2 w3){
;   float2 a0=Z[i0], a1=Z[i1], a2=Z[i2], a3=Z[i3];
;   if (INV && !NOTW){ a1=cmulc(a1,w1); a2=cmulc(a2,w2); a3=cmulc(a3,w3); }
;   float2 s02=make_float2(a0.x+a2.x,a0.y+a2.y), d02=make_float2(a0.x-a2.x,a0.y-a2.y);
;   float2 s13=make_float2(a1.x+a3.x,a1.y+a3.y), d13=make_float2(a1.x-a3.x,a1.y-a3.y);
;   float2 y0=make_float2(s02.x+s13.x,s02.y+s13.y), y2=make_float2(s02.x-s13.x,s02.y-s13.y);
;   float2 ym=make_float2(d02.x+d13.y,d02.y-d13.x);
;   float2 yp=make_float2(d02.x-d13.y,d02.y+d13.x);
;   float2 y1, y3;
;   if (INV){ y1=yp; y3=ym; } else if (NOTW){ y1=ym; y3=yp; } else { y1=cmul(ym,w1); y2=cmul(y2,w2); y3=cmul(yp,w3); }
;   Z[i0]=y0; Z[i1]=y1; Z[i2]=y2; Z[i3]=y3;
; template<bool INV, int LQ, bool BARRIER=true>
; HD void fft_pass(float2* Z, const float2* twA, const float2* twB, int tid){
;     ...
;     int j=tid&(q-1); int base0=((tid>>LQ)<<(LQ+2))+j;
;     float2 w1=make_float2(1.f,0.f), w2=w1, w3=w1;
;     if (LQ>0){ int k=j*tws; w1=cmul(twA[k>>6],twB[k&63]); w2=cmul(w1,w1); w3=cmul(w2,w1); }
;     _Pragma("unroll") for (int i=0;i<8;++i){ int base=base0+i*2048; bf4c<INV,(LQ==0)>(Z,base,base+q,base+2*q,base+3*q,w1,w2,w3); }
;   }
;   if (BARRIER) __syncthreads(); else asm volatile("s_waitcnt lgkmcnt(0)" ::: "memory");
	v_add_f32_e32 v22, v8, v12
	v_sub_f32_e32 v24, v8, v12
	v_add_f32_e32 v26, v10, v14
	v_sub_f32_e32 v28, v10, v14
	v_add_f32_e32 v23, v9, v13
	v_sub_f32_e32 v25, v9, v13
	v_add_f32_e32 v27, v11, v15
	v_sub_f32_e32 v29, v11, v15
	v_add_f32_e32 v80, v22, v26
	v_add_f32_e32 v81, v23, v27
	ds_write_b64 v222, v[80:81] offset:16384
	v_sub_f32_e32 v242, v22, v26
	v_sub_f32_e32 v243, v23, v27
	v_add_f32_e32 v244, v24, v29
	v_sub_f32_e32 v245, v25, v28
	v_sub_f32_e32 v246, v24, v29
	v_add_f32_e32 v247, v25, v28
	v_mul_f32_e32 v227, v245, v17
	v_fma_f32 v82, v244, v16, -v227
	v_mul_f32_e32 v227, v245, v16
	v_fma_f32 v83, v244, v17, v227
	ds_write_b64 v222, v[82:83] offset:16416
	v_mul_f32_e32 v227, v243, v19
	v_fma_f32 v84, v242, v18, -v227
	v_mul_f32_e32 v227, v243, v18
	v_fma_f32 v85, v242, v19, v227
	ds_write_b64 v222, v[84:85] offset:16448
	v_mul_f32_e32 v227, v247, v21
	v_fma_f32 v236, v246, v20, -v227
	v_mul_f32_e32 v227, v247, v20
	v_fma_f32 v237, v246, v21, v227
	ds_write_b64 v222, v[236:237] offset:16480
	ds_read_b64 v[8:9], v222 offset:49152
	ds_read_b64 v[10:11], v222 offset:49184
	ds_read_b64 v[12:13], v222 offset:49216
	ds_read_b64 v[14:15], v222 offset:49248
	s_waitcnt lgkmcnt(8)
	v_add_f32_e32 v22, v0, v4
	v_sub_f32_e32 v24, v0, v4
	v_add_f32_e32 v26, v2, v6
	v_sub_f32_e32 v28, v2, v6
	v_add_f32_e32 v23, v1, v5
	v_sub_f32_e32 v25, v1, v5
	v_add_f32_e32 v27, v3, v7
	v_sub_f32_e32 v29, v3, v7
	v_add_f32_e32 v80, v22, v26
	v_add_f32_e32 v81, v23, v27
	ds_write_b64 v222, v[80:81] offset:32768
	v_sub_f32_e32 v242, v22, v26
	v_sub_f32_e32 v243, v23, v27
	v_add_f32_e32 v244, v24, v29
	v_sub_f32_e32 v245, v25, v28
	v_sub_f32_e32 v246, v24, v29
	v_add_f32_e32 v247, v25, v28
	v_mul_f32_e32 v227, v245, v17
	v_fma_f32 v82, v244, v16, -v227
	v_mul_f32_e32 v227, v245, v16
	v_fma_f32 v83, v244, v17, v227
	ds_write_b64 v222, v[82:83] offset:32800
	v_mul_f32_e32 v227, v243, v19
	v_fma_f32 v84, v242, v18, -v227
	v_mul_f32_e32 v227, v243, v18
	v_fma_f32 v85, v242, v19, v227
	ds_write_b64 v222, v[84:85] offset:32832
	v_mul_f32_e32 v227, v247, v21
	v_fma_f32 v236, v246, v20, -v227
	v_mul_f32_e32 v227, v247, v20
	v_fma_f32 v237, v246, v21, v227
	ds_write_b64 v222, v[236:237] offset:32864
	ds_read_b64 v[0:1], v223 offset:0
	ds_read_b64 v[2:3], v223 offset:32
	ds_read_b64 v[4:5], v223 offset:64
	ds_read_b64 v[6:7], v223 offset:96
	s_waitcnt lgkmcnt(8)
	v_add_f32_e32 v22, v8, v12
	v_sub_f32_e32 v24, v8, v12
	v_add_f32_e32 v26, v10, v14
	v_sub_f32_e32 v28, v10, v14
	v_add_f32_e32 v23, v9, v13
	v_sub_f32_e32 v25, v9, v13
	v_add_f32_e32 v27, v11, v15
	v_sub_f32_e32 v29, v11, v15
	v_add_f32_e32 v80, v22, v26
	v_add_f32_e32 v81, v23, v27
	ds_write_b64 v222, v[80:81] offset:49152
	v_sub_f32_e32 v242, v22, v26
	v_sub_f32_e32 v243, v23, v27
	v_add_f32_e32 v244, v24, v29
	v_sub_f32_e32 v245, v25, v28
	v_sub_f32_e32 v246, v24, v29
	v_add_f32_e32 v247, v25, v28
	v_mul_f32_e32 v227, v245, v17
	v_fma_f32 v82, v244, v16, -v227
	v_mul_f32_e32 v227, v245, v16
	v_fma_f32 v83, v244, v17, v227
	ds_write_b64 v222, v[82:83] offset:49184
	v_mul_f32_e32 v227, v243, v19
	v_fma_f32 v84, v242, v18, -v227
	v_mul_f32_e32 v227, v243, v18
	v_fma_f32 v85, v242, v19, v227
	ds_write_b64 v222, v[84:85] offset:49216
	v_mul_f32_e32 v227, v247, v21
	v_fma_f32 v236, v246, v20, -v227
	v_mul_f32_e32 v227, v247, v20
	v_fma_f32 v237, v246, v21, v227
	ds_write_b64 v222, v[236:237] offset:49248
	ds_read_b64 v[8:9], v223 offset:16384
	ds_read_b64 v[10:11], v223 offset:16416
	ds_read_b64 v[12:13], v223 offset:16448
	ds_read_b64 v[14:15], v223 offset:16480
	s_waitcnt lgkmcnt(8)
	v_add_f32_e32 v22, v0, v4
	v_sub_f32_e32 v24, v0, v4
	v_add_f32_e32 v26, v2, v6
	v_sub_f32_e32 v28, v2, v6
	v_add_f32_e32 v23, v1, v5
	v_sub_f32_e32 v25, v1, v5
	v_add_f32_e32 v27, v3, v7
	v_sub_f32_e32 v29, v3, v7
	v_add_f32_e32 v80, v22, v26
	v_add_f32_e32 v81, v23, v27
	ds_write_b64 v223, v[80:81] offset:0
	v_sub_f32_e32 v242, v22, v26
	v_sub_f32_e32 v243, v23, v27
	v_add_f32_e32 v244, v24, v29
	v_sub_f32_e32 v245, v25, v28
	v_sub_f32_e32 v246, v24, v29
	v_add_f32_e32 v247, v25, v28
	v_mul_f32_e32 v227, v245, v17
	v_fma_f32 v82, v244, v16, -v227
	v_mul_f32_e32 v227, v245, v16
	v_fma_f32 v83, v244, v17, v227
	ds_write_b64 v223, v[82:83] offset:32
	v_mul_f32_e32 v227, v243, v19
	v_fma_f32 v84, v242, v18, -v227
	v_mul_f32_e32 v227, v243, v18
	v_fma_f32 v85, v242, v19, v227
	ds_write_b64 v223, v[84:85] offset:64
	v_mul_f32_e32 v227, v247, v21
	v_fma_f32 v236, v246, v20, -v227
	v_mul_f32_e32 v227, v247, v20
	v_fma_f32 v237, v246, v21, v227
	ds_write_b64 v223, v[236:237] offset:96
	ds_read_b64 v[0:1], v223 offset:32768
	ds_read_b64 v[2:3], v223 offset:32800
	ds_read_b64 v[4:5], v223 offset:32832
	ds_read_b64 v[6:7], v223 offset:32864
	s_waitcnt lgkmcnt(8)
	v_add_f32_e32 v22, v8, v12
	v_sub_f32_e32 v24, v8, v12
	v_add_f32_e32 v26, v10, v14
	v_sub_f32_e32 v28, v10, v14
	v_add_f32_e32 v23, v9, v13
	v_sub_f32_e32 v25, v9, v13
	v_add_f32_e32 v27, v11, v15
	v_sub_f32_e32 v29, v11, v15
	v_add_f32_e32 v80, v22, v26
	v_add_f32_e32 v81, v23, v27
	ds_write_b64 v223, v[80:81] offset:16384
	v_sub_f32_e32 v242, v22, v26
	v_sub_f32_e32 v243, v23, v27
	v_add_f32_e32 v244, v24, v29
	v_sub_f32_e32 v245, v25, v28
	v_sub_f32_e32 v246, v24, v29
	v_add_f32_e32 v247, v25, v28
	v_mul_f32_e32 v227, v245, v17
	v_fma_f32 v82, v244, v16, -v227
	v_mul_f32_e32 v227, v245, v16
	v_fma_f32 v83, v244, v17, v227
	ds_write_b64 v223, v[82:83] offset:16416
	v_mul_f32_e32 v227, v243, v19
	v_fma_f32 v84, v242, v18, -v227
	v_mul_f32_e32 v227, v243, v18
	v_fma_f32 v85, v242, v19, v227
	ds_write_b64 v223, v[84:85] offset:16448
	v_mul_f32_e32 v227, v247, v21
	v_fma_f32 v236, v246, v20, -v227
	v_mul_f32_e32 v227, v247, v20
	v_fma_f32 v237, v246, v21, v227
	ds_write_b64 v223, v[236:237] offset:16480
	ds_read_b64 v[8:9], v223 offset:49152
	ds_read_b64 v[10:11], v223 offset:49184
	ds_read_b64 v[12:13], v223 offset:49216
	ds_read_b64 v[14:15], v223 offset:49248
	s_waitcnt lgkmcnt(8)
; HD float2 cmul(float2 a, float2 b){ return make_float2(a.x*b.x - a.y*b.y, a.x*b.y + a.y*b.x); }
; template<bool INV, int LQ, bool BARRIER=true>
; HD void fft_pass(float2* Z, const float2* twA, const float2* twB, int tid){
;     ...
;     int j=tid&(q-1); int base0=((tid>>LQ)<<(LQ+2))+j;
;     float2 w1=make_float2(1.f,0.f), w2=w1, w3=w1;
;     if (LQ>0){ int k=j*tws; w1=cmul(twA[k>>6],twB[k&63]); w2=cmul(w1,w1); w3=cmul(w2,w1); }
;     _Pragma("unroll") for (int i=0;i<8;++i){ int base=base0+i*2048; bf4c<INV,(LQ==0)>(Z,base,base+q,base+2*q,base+3*q,w1,w2,w3); }
;   }
;   if (BARRIER) __syncthreads(); else asm volatile("s_waitcnt lgkmcnt(0)" ::: "memory");
; __device__ __forceinline__ void fft_mid(float2* Z, const f16x2* Hp, int tid){
;   _Pragma("unroll 4") for (int i=0;i<8;++i){ int base=(tid<<2)+i*2048;
;     u32x4 hw=*(const u32x4*)(Hp+base);
;     unsigned hw0=hw[0], hw1=hw[1], hw2=hw[2], hw3=hw[3];
;     float2 a0=Z[base], a1=Z[base+1], a2=Z[base+2], a3=Z[base+3];
;     float2 s02=make_float2(a0.x+a2.x,a0.y+a2.y), d02=make_float2(a0.x-a2.x,a0.y-a2.y);
;     float2 s13=make_float2(a1.x+a3.x,a1.y+a3.y), d13=make_float2(a1.x-a3.x,a1.y-a3.y);
;     float2 y0=make_float2(s02.x+s13.x,s02.y+s13.y), y2=make_float2(s02.x-s13.x,s02.y-s13.y);
;     float2 y1=make_float2(d02.x+d13.y,d02.y-d13.x);
;     float2 y3=make_float2(d02.x-d13.y,d02.y+d13.x);
;     f16x2 h0=__builtin_bit_cast(f16x2,hw0), h1=__builtin_bit_cast(f16x2,hw1), h2=__builtin_bit_cast(f16x2,hw2), h3=__builtin_bit_cast(f16x2,hw3);
;     float2 b0=cmul(y0,make_float2((float)h0[0],(float)h0[1])), b1=cmul(y1,make_float2((float)h1[0],(float)h1[1]));
;     float2 b2=cmul(y2,make_float2((float)h2[0],(float)h2[1])), b3=cmul(y3,make_float2((float)h3[0],(float)h3[1]));
;     float2 t02=make_float2(b0.x+b2.x,b0.y+b2.y), e02=make_float2(b0.x-b2.x,b0.y-b2.y);
;     float2 t13=make_float2(b1.x+b3.x,b1.y+b3.y), e13=make_float2(b1.x-b3.x,b1.y-b3.y);
;     Z[base]=make_float2(t02.x+t13.x,t02.y+t13.y); Z[base+2]=make_float2(t02.x-t13.x,t02.y-t13.y);
;     Z[base+1]=make_float2(e02.x-e13.y,e02.y+e13.x);
;     Z[base+3]=make_float2(e02.x+e13.y,e02.y-e13.x);
;   }
	v_add_f32_e32 v22, v0, v4
	v_sub_f32_e32 v24, v0, v4
	v_add_f32_e32 v26, v2, v6
	v_sub_f32_e32 v28, v2, v6
	v_add_f32_e32 v23, v1, v5
	v_sub_f32_e32 v25, v1, v5
	v_add_f32_e32 v27, v3, v7
	v_sub_f32_e32 v29, v3, v7
	v_add_f32_e32 v80, v22, v26
	v_add_f32_e32 v81, v23, v27
	ds_write_b64 v223, v[80:81] offset:32768
	v_sub_f32_e32 v242, v22, v26
	v_sub_f32_e32 v243, v23, v27
	v_add_f32_e32 v244, v24, v29
	v_sub_f32_e32 v245, v25, v28
	v_sub_f32_e32 v246, v24, v29
	v_add_f32_e32 v247, v25, v28
	v_mul_f32_e32 v227, v245, v17
	v_fma_f32 v82, v244, v16, -v227
	v_mul_f32_e32 v227, v245, v16
	v_fma_f32 v83, v244, v17, v227
	ds_write_b64 v223, v[82:83] offset:32800
	v_mul_f32_e32 v227, v243, v19
	v_fma_f32 v84, v242, v18, -v227
	v_mul_f32_e32 v227, v243, v18
	v_fma_f32 v85, v242, v19, v227
	ds_write_b64 v223, v[84:85] offset:32832
	v_mul_f32_e32 v227, v247, v21
	v_fma_f32 v236, v246, v20, -v227
	v_mul_f32_e32 v227, v247, v20
	v_fma_f32 v237, v246, v21, v227
	ds_write_b64 v223, v[236:237] offset:32864
	s_waitcnt lgkmcnt(4)
	v_add_f32_e32 v22, v8, v12
	v_sub_f32_e32 v24, v8, v12
	v_add_f32_e32 v26, v10, v14
	v_sub_f32_e32 v28, v10, v14
	v_add_f32_e32 v23, v9, v13
	v_sub_f32_e32 v25, v9, v13
	v_add_f32_e32 v27, v11, v15
	v_sub_f32_e32 v29, v11, v15
	v_add_f32_e32 v80, v22, v26
	v_add_f32_e32 v81, v23, v27
	ds_write_b64 v223, v[80:81] offset:49152
	v_sub_f32_e32 v242, v22, v26
	v_sub_f32_e32 v243, v23, v27
	v_add_f32_e32 v244, v24, v29
	v_sub_f32_e32 v245, v25, v28
	v_sub_f32_e32 v246, v24, v29
	v_add_f32_e32 v247, v25, v28
	v_mul_f32_e32 v227, v245, v17
	v_fma_f32 v82, v244, v16, -v227
	v_mul_f32_e32 v227, v245, v16
	v_fma_f32 v83, v244, v17, v227
	ds_write_b64 v223, v[82:83] offset:49184
	v_mul_f32_e32 v227, v243, v19
	v_fma_f32 v84, v242, v18, -v227
	v_mul_f32_e32 v227, v243, v18
	v_fma_f32 v85, v242, v19, v227
	ds_write_b64 v223, v[84:85] offset:49216
	v_mul_f32_e32 v227, v247, v21
	v_fma_f32 v236, v246, v20, -v227
	v_mul_f32_e32 v227, v247, v20
	v_fma_f32 v237, v246, v21, v227
	ds_write_b64 v223, v[236:237] offset:49248
	s_waitcnt lgkmcnt(0)
	v_add_u32_e32 v14, 0x4000, v169
	v_add_u32_e32 v15, 0x8000, v169
	v_add_u32_e32 v16, 0xc000, v169
	v_add_u32_e32 v17, 0x4000, v186
	v_add_u32_e32 v18, 0x8000, v186
	v_add_u32_e32 v19, 0xc000, v186
	s_mov_b64 s[12:13], -1
	s_and_b64 vcc, exec, s[68:69]
	s_cbranch_vccz .LBB0_1344
	s_cmp_lg_u32 s89, 1
	s_cselect_b64 s[50:51], -1, 0
	s_cmp_eq_u32 s89, 1
	s_cselect_b32 s69, s77, s79
	s_cselect_b32 s68, s76, s78
	v_lshlrev_b32_e32 v224, 4, v154
	v_lshlrev_b32_e32 v222, 5, v154
	v_add_u32_e32 v223, 0x10000, v222
	global_load_dwordx4 v[236:239], v224, s[68:69]
	s_add_u32 s98, s68, 0x2000
	s_addc_u32 s99, s69, 0
	global_load_dwordx4 v[240:243], v224, s[98:99]
	s_add_u32 s98, s68, 0x4000
	s_addc_u32 s99, s69, 0
	global_load_dwordx4 v[244:247], v224, s[98:99]
	s_add_u32 s98, s68, 0x6000
	s_addc_u32 s99, s69, 0
	global_load_dwordx4 v[248:251], v224, s[98:99]
	ds_read_b128 v[0:3], v222 offset:0
	ds_read_b128 v[4:7], v222 offset:16
	s_waitcnt vmcnt(3) lgkmcnt(0)
	v_add_f32_e32 v8, v0, v4
	v_sub_f32_e32 v10, v0, v4
	v_add_f32_e32 v12, v2, v6
	v_sub_f32_e32 v20, v2, v6
	v_add_f32_e32 v9, v1, v5
	v_sub_f32_e32 v11, v1, v5
	v_add_f32_e32 v13, v3, v7
	v_sub_f32_e32 v21, v3, v7
	v_add_f32_e32 v22, v8, v12
	v_add_f32_e32 v23, v9, v13
	v_sub_f32_e32 v26, v8, v12
	v_sub_f32_e32 v27, v9, v13
	v_add_f32_e32 v24, v10, v21
	v_sub_f32_e32 v25, v11, v20
	v_sub_f32_e32 v28, v10, v21
	v_add_f32_e32 v29, v11, v20
	v_cvt_f32_f16_e32 v30, v236
	v_cvt_f32_f16_sdwa v31, v236 dst_sel:DWORD dst_unused:UNUSED_PAD src0_sel:WORD_1
	s_nop 0
	v_mul_f32_e32 v0, v23, v31
	v_fma_f32 v0, v22, v30, -v0
	v_mul_f32_e32 v1, v23, v30
	v_fma_f32 v1, v22, v31, v1
	v_cvt_f32_f16_e32 v30, v237
	v_cvt_f32_f16_sdwa v31, v237 dst_sel:DWORD dst_unused:UNUSED_PAD src0_sel:WORD_1
	s_nop 0
	v_mul_f32_e32 v2, v25, v31
	v_fma_f32 v2, v24, v30, -v2
	v_mul_f32_e32 v3, v25, v30
	v_fma_f32 v3, v24, v31, v3
	v_cvt_f32_f16_e32 v30, v238
	v_cvt_f32_f16_sdwa v31, v238 dst_sel:DWORD dst_unused:UNUSED_PAD src0_sel:WORD_1
	s_nop 0
	v_mul_f32_e32 v4, v27, v31
	v_fma_f32 v4, v26, v30, -v4
	v_mul_f32_e32 v5, v27, v30
	v_fma_f32 v5, v26, v31, v5
	v_cvt_f32_f16_e32 v30, v239
	v_cvt_f32_f16_sdwa v31, v239 dst_sel:DWORD dst_unused:UNUSED_PAD src0_sel:WORD_1
	s_nop 0
	v_mul_f32_e32 v6, v29, v31
	v_fma_f32 v6, v28, v30, -v6
	v_mul_f32_e32 v7, v29, v30
	v_fma_f32 v7, v28, v31, v7
	v_add_f32_e32 v8, v0, v4
	v_sub_f32_e32 v10, v0, v4
	v_add_f32_e32 v12, v2, v6
	v_sub_f32_e32 v20, v2, v6
	v_add_f32_e32 v9, v1, v5
	v_sub_f32_e32 v11, v1, v5
	v_add_f32_e32 v13, v3, v7
	v_sub_f32_e32 v21, v3, v7
	v_add_f32_e32 v0, v8, v12
	v_add_f32_e32 v1, v9, v13
	v_sub_f32_e32 v2, v10, v21
	v_add_f32_e32 v3, v11, v20
	v_sub_f32_e32 v4, v8, v12
	v_sub_f32_e32 v5, v9, v13
	v_add_f32_e32 v6, v10, v21
	v_sub_f32_e32 v7, v11, v20
	ds_write_b128 v222, v[0:3] offset:0
	ds_write_b128 v222, v[4:7] offset:16
	ds_read_b128 v[0:3], v222 offset:16384
	ds_read_b128 v[4:7], v222 offset:16400
	s_waitcnt vmcnt(2) lgkmcnt(0)
; HD float2 cmul(float2 a, float2 b){ return make_float2(a.x*b.x - a.y*b.y, a.x*b.y + a.y*b.x); }
; __device__ __forceinline__ void fft_mid(float2* Z, const f16x2* Hp, int tid){
;   _Pragma("unroll 4") for (int i=0;i<8;++i){ int base=(tid<<2)+i*2048;
;     u32x4 hw=*(const u32x4*)(Hp+base);
;     unsigned hw0=hw[0], hw1=hw[1], hw2=hw[2], hw3=hw[3];
;     float2 a0=Z[base], a1=Z[base+1], a2=Z[base+2], a3=Z[base+3];
;     float2 s02=make_float2(a0.x+a2.x,a0.y+a2.y), d02=make_float2(a0.x-a2.x,a0.y-a2.y);
;     float2 s13=make_float2(a1.x+a3.x,a1.y+a3.y), d13=make_float2(a1.x-a3.x,a1.y-a3.y);
;     float2 y0=make_float2(s02.x+s13.x,s02.y+s13.y), y2=make_float2(s02.x-s13.x,s02.y-s13.y);
;     float2 y1=make_float2(d02.x+d13.y,d02.y-d13.x);
;     float2 y3=make_float2(d02.x-d13.y,d02.y+d13.x);
;     f16x2 h0=__builtin_bit_cast(f16x2,hw0), h1=__builtin_bit_cast(f16x2,hw1), h2=__builtin_bit_cast(f16x2,hw2), h3=__builtin_bit_cast(f16x2,hw3);
;     float2 b0=cmul(y0,make_float2((float)h0[0],(float)h0[1])), b1=cmul(y1,make_float2((float)h1[0],(float)h1[1]));
;     float2 b2=cmul(y2,make_float2((float)h2[0],(float)h2[1])), b3=cmul(y3,make_float2((float)h3[0],(float)h3[1]));
;     float2 t02=make_float2(b0.x+b2.x,b0.y+b2.y), e02=make_float2(b0.x-b2.x,b0.y-b2.y);
;     float2 t13=make_float2(b1.x+b3.x,b1.y+b3.y), e13=make_float2(b1.x-b3.x,b1.y-b3.y);
;     Z[base]=make_float2(t02.x+t13.x,t02.y+t13.y); Z[base+2]=make_float2(t02.x-t13.x,t02.y-t13.y);
;     Z[base+1]=make_float2(e02.x-e13.y,e02.y+e13.x);
;     Z[base+3]=make_float2(e02.x+e13.y,e02.y-e13.x);
;   }
	v_add_f32_e32 v8, v0, v4
	v_sub_f32_e32 v10, v0, v4
	v_add_f32_e32 v12, v2, v6
	v_sub_f32_e32 v20, v2, v6
	v_add_f32_e32 v9, v1, v5
	v_sub_f32_e32 v11, v1, v5
	v_add_f32_e32 v13, v3, v7
	v_sub_f32_e32 v21, v3, v7
	v_add_f32_e32 v22, v8, v12
	v_add_f32_e32 v23, v9, v13
	v_sub_f32_e32 v26, v8, v12
	v_sub_f32_e32 v27, v9, v13
	v_add_f32_e32 v24, v10, v21
	v_sub_f32_e32 v25, v11, v20
	v_sub_f32_e32 v28, v10, v21
	v_add_f32_e32 v29, v11, v20
	v_cvt_f32_f16_e32 v30, v240
	v_cvt_f32_f16_sdwa v31, v240 dst_sel:DWORD dst_unused:UNUSED_PAD src0_sel:WORD_1
	s_nop 0
	v_mul_f32_e32 v0, v23, v31
	v_fma_f32 v0, v22, v30, -v0
	v_mul_f32_e32 v1, v23, v30
	v_fma_f32 v1, v22, v31, v1
	v_cvt_f32_f16_e32 v30, v241
	v_cvt_f32_f16_sdwa v31, v241 dst_sel:DWORD dst_unused:UNUSED_PAD src0_sel:WORD_1
	s_nop 0
	v_mul_f32_e32 v2, v25, v31
	v_fma_f32 v2, v24, v30, -v2
	v_mul_f32_e32 v3, v25, v30
	v_fma_f32 v3, v24, v31, v3
	v_cvt_f32_f16_e32 v30, v242
	v_cvt_f32_f16_sdwa v31, v242 dst_sel:DWORD dst_unused:UNUSED_PAD src0_sel:WORD_1
	s_nop 0
	v_mul_f32_e32 v4, v27, v31
	v_fma_f32 v4, v26, v30, -v4
	v_mul_f32_e32 v5, v27, v30
	v_fma_f32 v5, v26, v31, v5
	v_cvt_f32_f16_e32 v30, v243
	v_cvt_f32_f16_sdwa v31, v243 dst_sel:DWORD dst_unused:UNUSED_PAD src0_sel:WORD_1
	s_nop 0
	v_mul_f32_e32 v6, v29, v31
	v_fma_f32 v6, v28, v30, -v6
	v_mul_f32_e32 v7, v29, v30
	v_fma_f32 v7, v28, v31, v7
	v_add_f32_e32 v8, v0, v4
	v_sub_f32_e32 v10, v0, v4
	v_add_f32_e32 v12, v2, v6
	v_sub_f32_e32 v20, v2, v6
	v_add_f32_e32 v9, v1, v5
	v_sub_f32_e32 v11, v1, v5
	v_add_f32_e32 v13, v3, v7
	v_sub_f32_e32 v21, v3, v7
	v_add_f32_e32 v0, v8, v12
	v_add_f32_e32 v1, v9, v13
	v_sub_f32_e32 v2, v10, v21
	v_add_f32_e32 v3, v11, v20
	v_sub_f32_e32 v4, v8, v12
	v_sub_f32_e32 v5, v9, v13
	v_add_f32_e32 v6, v10, v21
	v_sub_f32_e32 v7, v11, v20
	ds_write_b128 v222, v[0:3] offset:16384
	ds_write_b128 v222, v[4:7] offset:16400
	ds_read_b128 v[0:3], v222 offset:32768
	ds_read_b128 v[4:7], v222 offset:32784
	s_waitcnt vmcnt(1) lgkmcnt(0)
	v_add_f32_e32 v8, v0, v4
	v_sub_f32_e32 v10, v0, v4
	v_add_f32_e32 v12, v2, v6
	v_sub_f32_e32 v20, v2, v6
	v_add_f32_e32 v9, v1, v5
	v_sub_f32_e32 v11, v1, v5
	v_add_f32_e32 v13, v3, v7
	v_sub_f32_e32 v21, v3, v7
	v_add_f32_e32 v22, v8, v12
	v_add_f32_e32 v23, v9, v13
	v_sub_f32_e32 v26, v8, v12
	v_sub_f32_e32 v27, v9, v13
	v_add_f32_e32 v24, v10, v21
	v_sub_f32_e32 v25, v11, v20
	v_sub_f32_e32 v28, v10, v21
	v_add_f32_e32 v29, v11, v20
	v_cvt_f32_f16_e32 v30, v244
	v_cvt_f32_f16_sdwa v31, v244 dst_sel:DWORD dst_unused:UNUSED_PAD src0_sel:WORD_1
	s_nop 0
	v_mul_f32_e32 v0, v23, v31
	v_fma_f32 v0, v22, v30, -v0
	v_mul_f32_e32 v1, v23, v30
	v_fma_f32 v1, v22, v31, v1
	v_cvt_f32_f16_e32 v30, v245
	v_cvt_f32_f16_sdwa v31, v245 dst_sel:DWORD dst_unused:UNUSED_PAD src0_sel:WORD_1
	s_nop 0
	v_mul_f32_e32 v2, v25, v31
	v_fma_f32 v2, v24, v30, -v2
	v_mul_f32_e32 v3, v25, v30
	v_fma_f32 v3, v24, v31, v3
	v_cvt_f32_f16_e32 v30, v246
	v_cvt_f32_f16_sdwa v31, v246 dst_sel:DWORD dst_unused:UNUSED_PAD src0_sel:WORD_1
	s_nop 0
	v_mul_f32_e32 v4, v27, v31
	v_fma_f32 v4, v26, v30, -v4
	v_mul_f32_e32 v5, v27, v30
	v_fma_f32 v5, v26, v31, v5
	v_cvt_f32_f16_e32 v30, v247
	v_cvt_f32_f16_sdwa v31, v247 dst_sel:DWORD dst_unused:UNUSED_PAD src0_sel:WORD_1
	s_nop 0
	v_mul_f32_e32 v6, v29, v31
	v_fma_f32 v6, v28, v30, -v6
	v_mul_f32_e32 v7, v29, v30
	v_fma_f32 v7, v28, v31, v7
	v_add_f32_e32 v8, v0, v4
	v_sub_f32_e32 v10, v0, v4
	v_add_f32_e32 v12, v2, v6
	v_sub_f32_e32 v20, v2, v6
	v_add_f32_e32 v9, v1, v5
	v_sub_f32_e32 v11, v1, v5
	v_add_f32_e32 v13, v3, v7
	v_sub_f32_e32 v21, v3, v7
	v_add_f32_e32 v0, v8, v12
	v_add_f32_e32 v1, v9, v13
	v_sub_f32_e32 v2, v10, v21
	v_add_f32_e32 v3, v11, v20
	v_sub_f32_e32 v4, v8, v12
	v_sub_f32_e32 v5, v9, v13
	v_add_f32_e32 v6, v10, v21
	v_sub_f32_e32 v7, v11, v20
	ds_write_b128 v222, v[0:3] offset:32768
	ds_write_b128 v222, v[4:7] offset:32784
	ds_read_b128 v[0:3], v222 offset:49152
	ds_read_b128 v[4:7], v222 offset:49168
	s_waitcnt vmcnt(0) lgkmcnt(0)
	v_add_f32_e32 v8, v0, v4
	v_sub_f32_e32 v10, v0, v4
	v_add_f32_e32 v12, v2, v6
	v_sub_f32_e32 v20, v2, v6
	v_add_f32_e32 v9, v1, v5
	v_sub_f32_e32 v11, v1, v5
	v_add_f32_e32 v13, v3, v7
	v_sub_f32_e32 v21, v3, v7
	v_add_f32_e32 v22, v8, v12
	v_add_f32_e32 v23, v9, v13
	v_sub_f32_e32 v26, v8, v12
	v_sub_f32_e32 v27, v9, v13
	v_add_f32_e32 v24, v10, v21
	v_sub_f32_e32 v25, v11, v20
	v_sub_f32_e32 v28, v10, v21
	v_add_f32_e32 v29, v11, v20
	v_cvt_f32_f16_e32 v30, v248
	v_cvt_f32_f16_sdwa v31, v248 dst_sel:DWORD dst_unused:UNUSED_PAD src0_sel:WORD_1
	s_nop 0
	v_mul_f32_e32 v0, v23, v31
	v_fma_f32 v0, v22, v30, -v0
	v_mul_f32_e32 v1, v23, v30
	v_fma_f32 v1, v22, v31, v1
	v_cvt_f32_f16_e32 v30, v249
	v_cvt_f32_f16_sdwa v31, v249 dst_sel:DWORD dst_unused:UNUSED_PAD src0_sel:WORD_1
	s_nop 0
	v_mul_f32_e32 v2, v25, v31
	v_fma_f32 v2, v24, v30, -v2
	v_mul_f32_e32 v3, v25, v30
	v_fma_f32 v3, v24, v31, v3
	v_cvt_f32_f16_e32 v30, v250
	v_cvt_f32_f16_sdwa v31, v250 dst_sel:DWORD dst_unused:UNUSED_PAD src0_sel:WORD_1
	s_nop 0
	v_mul_f32_e32 v4, v27, v31
	v_fma_f32 v4, v26, v30, -v4
	v_mul_f32_e32 v5, v27, v30
	v_fma_f32 v5, v26, v31, v5
	v_cvt_f32_f16_e32 v30, v251
	v_cvt_f32_f16_sdwa v31, v251 dst_sel:DWORD dst_unused:UNUSED_PAD src0_sel:WORD_1
	s_nop 0
	v_mul_f32_e32 v6, v29, v31
	v_fma_f32 v6, v28, v30, -v6
	v_mul_f32_e32 v7, v29, v30
	v_fma_f32 v7, v28, v31, v7
	v_add_f32_e32 v8, v0, v4
	v_sub_f32_e32 v10, v0, v4
	v_add_f32_e32 v12, v2, v6
	v_sub_f32_e32 v20, v2, v6
	v_add_f32_e32 v9, v1, v5
	v_sub_f32_e32 v11, v1, v5
	v_add_f32_e32 v13, v3, v7
	v_sub_f32_e32 v21, v3, v7
	v_add_f32_e32 v0, v8, v12
	v_add_f32_e32 v1, v9, v13
	v_sub_f32_e32 v2, v10, v21
	v_add_f32_e32 v3, v11, v20
	v_sub_f32_e32 v4, v8, v12
	v_sub_f32_e32 v5, v9, v13
	v_add_f32_e32 v6, v10, v21
	v_sub_f32_e32 v7, v11, v20
	ds_write_b128 v222, v[0:3] offset:49152
	ds_write_b128 v222, v[4:7] offset:49168
	s_add_u32 s98, s68, 0x8000
	s_addc_u32 s99, s69, 0
	global_load_dwordx4 v[236:239], v224, s[98:99]
	s_add_u32 s98, s68, 0xa000
	s_addc_u32 s99, s69, 0
	global_load_dwordx4 v[240:243], v224, s[98:99]
	s_add_u32 s98, s68, 0xc000
	s_addc_u32 s99, s69, 0
	global_load_dwordx4 v[244:247], v224, s[98:99]
	s_add_u32 s98, s68, 0xe000
	s_addc_u32 s99, s69, 0
	global_load_dwordx4 v[248:251], v224, s[98:99]
	ds_read_b128 v[0:3], v223 offset:0
	ds_read_b128 v[4:7], v223 offset:16
	s_waitcnt vmcnt(3) lgkmcnt(0)
; HD float2 cmul(float2 a, float2 b){ return make_float2(a.x*b.x - a.y*b.y, a.x*b.y + a.y*b.x); }
; __device__ __forceinline__ void fft_mid(float2* Z, const f16x2* Hp, int tid){
;   _Pragma("unroll 4") for (int i=0;i<8;++i){ int base=(tid<<2)+i*2048;
;     u32x4 hw=*(const u32x4*)(Hp+base);
;     unsigned hw0=hw[0], hw1=hw[1], hw2=hw[2], hw3=hw[3];
;     float2 a0=Z[base], a1=Z[base+1], a2=Z[base+2], a3=Z[base+3];
;     float2 s02=make_float2(a0.x+a2.x,a0.y+a2.y), d02=make_float2(a0.x-a2.x,a0.y-a2.y);
;     float2 s13=make_float2(a1.x+a3.x,a1.y+a3.y), d13=make_float2(a1.x-a3.x,a1.y-a3.y);
;     float2 y0=make_float2(s02.x+s13.x,s02.y+s13.y), y2=make_float2(s02.x-s13.x,s02.y-s13.y);
;     float2 y1=make_float2(d02.x+d13.y,d02.y-d13.x);
;     float2 y3=make_float2(d02.x-d13.y,d02.y+d13.x);
;     f16x2 h0=__builtin_bit_cast(f16x2,hw0), h1=__builtin_bit_cast(f16x2,hw1), h2=__builtin_bit_cast(f16x2,hw2), h3=__builtin_bit_cast(f16x2,hw3);
;     float2 b0=cmul(y0,make_float2((float)h0[0],(float)h0[1])), b1=cmul(y1,make_float2((float)h1[0],(float)h1[1]));
;     float2 b2=cmul(y2,make_float2((float)h2[0],(float)h2[1])), b3=cmul(y3,make_float2((float)h3[0],(float)h3[1]));
;     float2 t02=make_float2(b0.x+b2.x,b0.y+b2.y), e02=make_float2(b0.x-b2.x,b0.y-b2.y);
;     float2 t13=make_float2(b1.x+b3.x,b1.y+b3.y), e13=make_float2(b1.x-b3.x,b1.y-b3.y);
;     Z[base]=make_float2(t02.x+t13.x,t02.y+t13.y); Z[base+2]=make_float2(t02.x-t13.x,t02.y-t13.y);
;     Z[base+1]=make_float2(e02.x-e13.y,e02.y+e13.x);
;     Z[base+3]=make_float2(e02.x+e13.y,e02.y-e13.x);
;   }
	v_add_f32_e32 v8, v0, v4
	v_sub_f32_e32 v10, v0, v4
	v_add_f32_e32 v12, v2, v6
	v_sub_f32_e32 v20, v2, v6
	v_add_f32_e32 v9, v1, v5
	v_sub_f32_e32 v11, v1, v5
	v_add_f32_e32 v13, v3, v7
	v_sub_f32_e32 v21, v3, v7
	v_add_f32_e32 v22, v8, v12
	v_add_f32_e32 v23, v9, v13
	v_sub_f32_e32 v26, v8, v12
	v_sub_f32_e32 v27, v9, v13
	v_add_f32_e32 v24, v10, v21
	v_sub_f32_e32 v25, v11, v20
	v_sub_f32_e32 v28, v10, v21
	v_add_f32_e32 v29, v11, v20
	v_cvt_f32_f16_e32 v30, v236
	v_cvt_f32_f16_sdwa v31, v236 dst_sel:DWORD dst_unused:UNUSED_PAD src0_sel:WORD_1
	s_nop 0
	v_mul_f32_e32 v0, v23, v31
	v_fma_f32 v0, v22, v30, -v0
	v_mul_f32_e32 v1, v23, v30
	v_fma_f32 v1, v22, v31, v1
	v_cvt_f32_f16_e32 v30, v237
	v_cvt_f32_f16_sdwa v31, v237 dst_sel:DWORD dst_unused:UNUSED_PAD src0_sel:WORD_1
	s_nop 0
	v_mul_f32_e32 v2, v25, v31
	v_fma_f32 v2, v24, v30, -v2
	v_mul_f32_e32 v3, v25, v30
	v_fma_f32 v3, v24, v31, v3
	v_cvt_f32_f16_e32 v30, v238
	v_cvt_f32_f16_sdwa v31, v238 dst_sel:DWORD dst_unused:UNUSED_PAD src0_sel:WORD_1
	s_nop 0
	v_mul_f32_e32 v4, v27, v31
	v_fma_f32 v4, v26, v30, -v4
	v_mul_f32_e32 v5, v27, v30
	v_fma_f32 v5, v26, v31, v5
	v_cvt_f32_f16_e32 v30, v239
	v_cvt_f32_f16_sdwa v31, v239 dst_sel:DWORD dst_unused:UNUSED_PAD src0_sel:WORD_1
	s_nop 0
	v_mul_f32_e32 v6, v29, v31
	v_fma_f32 v6, v28, v30, -v6
	v_mul_f32_e32 v7, v29, v30
	v_fma_f32 v7, v28, v31, v7
	v_add_f32_e32 v8, v0, v4
	v_sub_f32_e32 v10, v0, v4
	v_add_f32_e32 v12, v2, v6
	v_sub_f32_e32 v20, v2, v6
	v_add_f32_e32 v9, v1, v5
	v_sub_f32_e32 v11, v1, v5
	v_add_f32_e32 v13, v3, v7
	v_sub_f32_e32 v21, v3, v7
	v_add_f32_e32 v0, v8, v12
	v_add_f32_e32 v1, v9, v13
	v_sub_f32_e32 v2, v10, v21
	v_add_f32_e32 v3, v11, v20
	v_sub_f32_e32 v4, v8, v12
	v_sub_f32_e32 v5, v9, v13
	v_add_f32_e32 v6, v10, v21
	v_sub_f32_e32 v7, v11, v20
	ds_write_b128 v223, v[0:3] offset:0
	ds_write_b128 v223, v[4:7] offset:16
	ds_read_b128 v[0:3], v223 offset:16384
	ds_read_b128 v[4:7], v223 offset:16400
	s_waitcnt vmcnt(2) lgkmcnt(0)
	v_add_f32_e32 v8, v0, v4
	v_sub_f32_e32 v10, v0, v4
	v_add_f32_e32 v12, v2, v6
	v_sub_f32_e32 v20, v2, v6
	v_add_f32_e32 v9, v1, v5
	v_sub_f32_e32 v11, v1, v5
	v_add_f32_e32 v13, v3, v7
	v_sub_f32_e32 v21, v3, v7
	v_add_f32_e32 v22, v8, v12
	v_add_f32_e32 v23, v9, v13
	v_sub_f32_e32 v26, v8, v12
	v_sub_f32_e32 v27, v9, v13
	v_add_f32_e32 v24, v10, v21
	v_sub_f32_e32 v25, v11, v20
	v_sub_f32_e32 v28, v10, v21
	v_add_f32_e32 v29, v11, v20
	v_cvt_f32_f16_e32 v30, v240
	v_cvt_f32_f16_sdwa v31, v240 dst_sel:DWORD dst_unused:UNUSED_PAD src0_sel:WORD_1
	s_nop 0
	v_mul_f32_e32 v0, v23, v31
	v_fma_f32 v0, v22, v30, -v0
	v_mul_f32_e32 v1, v23, v30
	v_fma_f32 v1, v22, v31, v1
	v_cvt_f32_f16_e32 v30, v241
	v_cvt_f32_f16_sdwa v31, v241 dst_sel:DWORD dst_unused:UNUSED_PAD src0_sel:WORD_1
	s_nop 0
	v_mul_f32_e32 v2, v25, v31
	v_fma_f32 v2, v24, v30, -v2
	v_mul_f32_e32 v3, v25, v30
	v_fma_f32 v3, v24, v31, v3
	v_cvt_f32_f16_e32 v30, v242
	v_cvt_f32_f16_sdwa v31, v242 dst_sel:DWORD dst_unused:UNUSED_PAD src0_sel:WORD_1
	s_nop 0
	v_mul_f32_e32 v4, v27, v31
	v_fma_f32 v4, v26, v30, -v4
	v_mul_f32_e32 v5, v27, v30
	v_fma_f32 v5, v26, v31, v5
	v_cvt_f32_f16_e32 v30, v243
	v_cvt_f32_f16_sdwa v31, v243 dst_sel:DWORD dst_unused:UNUSED_PAD src0_sel:WORD_1
	s_nop 0
	v_mul_f32_e32 v6, v29, v31
	v_fma_f32 v6, v28, v30, -v6
	v_mul_f32_e32 v7, v29, v30
	v_fma_f32 v7, v28, v31, v7
	v_add_f32_e32 v8, v0, v4
	v_sub_f32_e32 v10, v0, v4
	v_add_f32_e32 v12, v2, v6
	v_sub_f32_e32 v20, v2, v6
	v_add_f32_e32 v9, v1, v5
	v_sub_f32_e32 v11, v1, v5
	v_add_f32_e32 v13, v3, v7
	v_sub_f32_e32 v21, v3, v7
	v_add_f32_e32 v0, v8, v12
	v_add_f32_e32 v1, v9, v13
	v_sub_f32_e32 v2, v10, v21
	v_add_f32_e32 v3, v11, v20
	v_sub_f32_e32 v4, v8, v12
	v_sub_f32_e32 v5, v9, v13
	v_add_f32_e32 v6, v10, v21
	v_sub_f32_e32 v7, v11, v20
	ds_write_b128 v223, v[0:3] offset:16384
	ds_write_b128 v223, v[4:7] offset:16400
	ds_read_b128 v[0:3], v223 offset:32768
	ds_read_b128 v[4:7], v223 offset:32784
	s_waitcnt vmcnt(1) lgkmcnt(0)
; HD float2 cmul(float2 a, float2 b){ return make_float2(a.x*b.x - a.y*b.y, a.x*b.y + a.y*b.x); }
; __device__ __forceinline__ void fft_mid(float2* Z, const f16x2* Hp, int tid){
;   _Pragma("unroll 4") for (int i=0;i<8;++i){ int base=(tid<<2)+i*2048;
;     u32x4 hw=*(const u32x4*)(Hp+base);
;     unsigned hw0=hw[0], hw1=hw[1], hw2=hw[2], hw3=hw[3];
;     float2 a0=Z[base], a1=Z[base+1], a2=Z[base+2], a3=Z[base+3];
;     float2 s02=make_float2(a0.x+a2.x,a0.y+a2.y), d02=make_float2(a0.x-a2.x,a0.y-a2.y);
;     float2 s13=make_float2(a1.x+a3.x,a1.y+a3.y), d13=make_float2(a1.x-a3.x,a1.y-a3.y);
;     float2 y0=make_float2(s02.x+s13.x,s02.y+s13.y), y2=make_float2(s02.x-s13.x,s02.y-s13.y);
;     float2 y1=make_float2(d02.x+d13.y,d02.y-d13.x);
;     float2 y3=make_float2(d02.x-d13.y,d02.y+d13.x);
;     f16x2 h0=__builtin_bit_cast(f16x2,hw0), h1=__builtin_bit_cast(f16x2,hw1), h2=__builtin_bit_cast(f16x2,hw2), h3=__builtin_bit_cast(f16x2,hw3);
;     float2 b0=cmul(y0,make_float2((float)h0[0],(float)h0[1])), b1=cmul(y1,make_float2((float)h1[0],(float)h1[1]));
;     float2 b2=cmul(y2,make_float2((float)h2[0],(float)h2[1])), b3=cmul(y3,make_float2((float)h3[0],(float)h3[1]));
;     float2 t02=make_float2(b0.x+b2.x,b0.y+b2.y), e02=make_float2(b0.x-b2.x,b0.y-b2.y);
;     float2 t13=make_float2(b1.x+b3.x,b1.y+b3.y), e13=make_float2(b1.x-b3.x,b1.y-b3.y);
;     Z[base]=make_float2(t02.x+t13.x,t02.y+t13.y); Z[base+2]=make_float2(t02.x-t13.x,t02.y-t13.y);
;     Z[base+1]=make_float2(e02.x-e13.y,e02.y+e13.x);
;     Z[base+3]=make_float2(e02.x+e13.y,e02.y-e13.x);
;   }
;   asm volatile("s_waitcnt lgkmcnt(0)" ::: "memory");
; __device__ __forceinline__ void phase_hyena(KP kp_, int hf){ asm volatile("" : "+s"(kp_)); const Params p=load_params(kp_);
;     ...
;         if (st==1){ int tq=tid; asm volatile("" : "+v"(tq));
;           _Pragma("unroll 4") for (int i=0;i<8;++i){ int tb=tq+512*i; float2 xr[2]; inv12_half(Z,twA,twB,tb,xr[0],xr[1]);
;             _Pragma("unroll") for (int hh=0;hh<2;++hh){ int t=tb+hh*4096;
;               float u0=hconv3(rv,t,wv0,wv1,wv2,bv_), u1=hconv3(rv+8192,t,wv0,wv1,wv2,bv_);
;               float x0=hconv3(r1,t,wa0,wa1,wa2,ba_), x1=hconv3(r1+8192,t,wa0,wa1,wa2,ba_);
;               float2 y=xr[hh]; y.x*=(1.f/16384.f); y.y*=(1.f/16384.f);
;               Zs[t]=make_float2(x0*(y.x+u0*bias0), x1*(y.y+u1*bias0)); } }
	v_add_f32_e32 v8, v0, v4
	v_sub_f32_e32 v10, v0, v4
	v_add_f32_e32 v12, v2, v6
	v_sub_f32_e32 v20, v2, v6
	v_add_f32_e32 v9, v1, v5
	v_sub_f32_e32 v11, v1, v5
	v_add_f32_e32 v13, v3, v7
	v_sub_f32_e32 v21, v3, v7
	v_add_f32_e32 v22, v8, v12
	v_add_f32_e32 v23, v9, v13
	v_sub_f32_e32 v26, v8, v12
	v_sub_f32_e32 v27, v9, v13
	v_add_f32_e32 v24, v10, v21
	v_sub_f32_e32 v25, v11, v20
	v_sub_f32_e32 v28, v10, v21
	v_add_f32_e32 v29, v11, v20
	v_cvt_f32_f16_e32 v30, v244
	v_cvt_f32_f16_sdwa v31, v244 dst_sel:DWORD dst_unused:UNUSED_PAD src0_sel:WORD_1
	s_nop 0
	v_mul_f32_e32 v0, v23, v31
	v_fma_f32 v0, v22, v30, -v0
	v_mul_f32_e32 v1, v23, v30
	v_fma_f32 v1, v22, v31, v1
	v_cvt_f32_f16_e32 v30, v245
	v_cvt_f32_f16_sdwa v31, v245 dst_sel:DWORD dst_unused:UNUSED_PAD src0_sel:WORD_1
	s_nop 0
	v_mul_f32_e32 v2, v25, v31
	v_fma_f32 v2, v24, v30, -v2
	v_mul_f32_e32 v3, v25, v30
	v_fma_f32 v3, v24, v31, v3
	v_cvt_f32_f16_e32 v30, v246
	v_cvt_f32_f16_sdwa v31, v246 dst_sel:DWORD dst_unused:UNUSED_PAD src0_sel:WORD_1
	s_nop 0
	v_mul_f32_e32 v4, v27, v31
	v_fma_f32 v4, v26, v30, -v4
	v_mul_f32_e32 v5, v27, v30
	v_fma_f32 v5, v26, v31, v5
	v_cvt_f32_f16_e32 v30, v247
	v_cvt_f32_f16_sdwa v31, v247 dst_sel:DWORD dst_unused:UNUSED_PAD src0_sel:WORD_1
	s_nop 0
	v_mul_f32_e32 v6, v29, v31
	v_fma_f32 v6, v28, v30, -v6
	v_mul_f32_e32 v7, v29, v30
	v_fma_f32 v7, v28, v31, v7
	v_add_f32_e32 v8, v0, v4
	v_sub_f32_e32 v10, v0, v4
	v_add_f32_e32 v12, v2, v6
	v_sub_f32_e32 v20, v2, v6
	v_add_f32_e32 v9, v1, v5
	v_sub_f32_e32 v11, v1, v5
	v_add_f32_e32 v13, v3, v7
	v_sub_f32_e32 v21, v3, v7
	v_add_f32_e32 v0, v8, v12
	v_add_f32_e32 v1, v9, v13
	v_sub_f32_e32 v2, v10, v21
	v_add_f32_e32 v3, v11, v20
	v_sub_f32_e32 v4, v8, v12
	v_sub_f32_e32 v5, v9, v13
	v_add_f32_e32 v6, v10, v21
	v_sub_f32_e32 v7, v11, v20
	ds_write_b128 v223, v[0:3] offset:32768
	ds_write_b128 v223, v[4:7] offset:32784
	ds_read_b128 v[0:3], v223 offset:49152
	ds_read_b128 v[4:7], v223 offset:49168
	s_waitcnt vmcnt(0) lgkmcnt(0)
	v_add_f32_e32 v8, v0, v4
	v_sub_f32_e32 v10, v0, v4
	v_add_f32_e32 v12, v2, v6
	v_sub_f32_e32 v20, v2, v6
	v_add_f32_e32 v9, v1, v5
	v_sub_f32_e32 v11, v1, v5
	v_add_f32_e32 v13, v3, v7
	v_sub_f32_e32 v21, v3, v7
	v_add_f32_e32 v22, v8, v12
	v_add_f32_e32 v23, v9, v13
	v_sub_f32_e32 v26, v8, v12
	v_sub_f32_e32 v27, v9, v13
	v_add_f32_e32 v24, v10, v21
	v_sub_f32_e32 v25, v11, v20
	v_sub_f32_e32 v28, v10, v21
	v_add_f32_e32 v29, v11, v20
	v_cvt_f32_f16_e32 v30, v248
	v_cvt_f32_f16_sdwa v31, v248 dst_sel:DWORD dst_unused:UNUSED_PAD src0_sel:WORD_1
	s_nop 0
	v_mul_f32_e32 v0, v23, v31
	v_fma_f32 v0, v22, v30, -v0
	v_mul_f32_e32 v1, v23, v30
	v_fma_f32 v1, v22, v31, v1
	v_cvt_f32_f16_e32 v30, v249
	v_cvt_f32_f16_sdwa v31, v249 dst_sel:DWORD dst_unused:UNUSED_PAD src0_sel:WORD_1
	s_nop 0
	v_mul_f32_e32 v2, v25, v31
	v_fma_f32 v2, v24, v30, -v2
	v_mul_f32_e32 v3, v25, v30
	v_fma_f32 v3, v24, v31, v3
	v_cvt_f32_f16_e32 v30, v250
	v_cvt_f32_f16_sdwa v31, v250 dst_sel:DWORD dst_unused:UNUSED_PAD src0_sel:WORD_1
	s_nop 0
	v_mul_f32_e32 v4, v27, v31
	v_fma_f32 v4, v26, v30, -v4
	v_mul_f32_e32 v5, v27, v30
	v_fma_f32 v5, v26, v31, v5
	v_cvt_f32_f16_e32 v30, v251
	v_cvt_f32_f16_sdwa v31, v251 dst_sel:DWORD dst_unused:UNUSED_PAD src0_sel:WORD_1
	s_nop 0
	v_mul_f32_e32 v6, v29, v31
	v_fma_f32 v6, v28, v30, -v6
	v_mul_f32_e32 v7, v29, v30
	v_fma_f32 v7, v28, v31, v7
	v_add_f32_e32 v8, v0, v4
	v_sub_f32_e32 v10, v0, v4
	v_add_f32_e32 v12, v2, v6
	v_sub_f32_e32 v20, v2, v6
	v_add_f32_e32 v9, v1, v5
	v_sub_f32_e32 v11, v1, v5
	v_add_f32_e32 v13, v3, v7
	v_sub_f32_e32 v21, v3, v7
	v_add_f32_e32 v0, v8, v12
	v_add_f32_e32 v1, v9, v13
	v_sub_f32_e32 v2, v10, v21
	v_add_f32_e32 v3, v11, v20
	v_sub_f32_e32 v4, v8, v12
	v_sub_f32_e32 v5, v9, v13
	v_add_f32_e32 v6, v10, v21
	v_sub_f32_e32 v7, v11, v20
	ds_write_b128 v223, v[0:3] offset:49152
	ds_write_b128 v223, v[4:7] offset:49168
	s_waitcnt lgkmcnt(0)
	s_mov_b64 s[18:19], 0x8000
	v_lshlrev_b32_e32 v232, 4, v154
	s_lshl_b32 s100, s90, 15
	v_add_u32_e32 v233, 0x2000, v232
	v_add_u32_e32 v234, 0x4000, v232
	v_add_u32_e32 v235, 0x6000, v232
	s_add_u32 s98, s70, 0x42bd000
	s_addc_u32 s99, s71, 0
	s_add_u32 s98, s98, s100
	s_addc_u32 s99, s99, 0
	s_cmp_eq_u32 s89, 1
	s_cbranch_scc1 .Lmy_pf_st1
	s_add_u32 s98, s98, 0x2000000
	s_addc_u32 s99, s99, 0
